# v40 + remaining VGPR-address LDS-DMAs in P6/P7/P8 K-loops converted (in-place base add moved behind the DMA; base copy in s[98:99])
# baseline (speedup 1.0000x reference)
.LBB0_1629:
	s_cmp_lg_u32 s100, 0
	s_cbranch_scc1 .Lpeel_4
	ds_read_b128 v[90:93], v211
	ds_read_b128 v[102:105], v212
	ds_read_b128 v[114:117], v213
	ds_read_b128 v[126:129], v214
	ds_read_b128 v[138:141], v215
	ds_read_b128 v[150:153], v216
	ds_read_b128 v[154:157], v217
	ds_read_b128 v[158:161], v218
	s_add_u32 s26, s24, 0xfffc0080
	s_addc_u32 s27, s25, -1
	s_cmp_eq_u32 s57, 12
	s_cselect_b32 s29, s15, s27
	s_cselect_b32 s28, s21, s26
	s_cselect_b32 s27, s13, s56
	s_cselect_b32 s26, s23, s55
	s_add_i32 m0, s41, 0xc000
	ds_read_b128 v[162:165], v219
	ds_read_b128 v[166:169], v219 offset:2048
	ds_read_b128 v[170:173], v220
	ds_read_b128 v[174:177], v220 offset:2048
	ds_read_b128 v[178:181], v219 offset:4096
	ds_read_b128 v[182:185], v219 offset:6144
	ds_read_b128 v[204:207], v220 offset:4096
	ds_read_b128 v[226:229], v220 offset:6144
	global_load_lds_dwordx4 v196, s[24:25]
	s_add_i32 m0, s41, 0xe000
	s_nop 0
	global_load_lds_dwordx4 v198, s[24:25]
	s_waitcnt vmcnt(8)
	s_waitcnt lgkmcnt(0)
	s_barrier
	s_setprio 1
	s_waitcnt lgkmcnt(0)
	v_mfma_f32_16x16x32_bf16 v[146:149], v[90:93], v[162:165], v[146:149]
	v_mfma_f32_16x16x32_bf16 v[142:145], v[114:117], v[162:165], v[142:145]
	v_mfma_f32_16x16x32_bf16 v[122:125], v[90:93], v[166:169], v[122:125]
	v_mfma_f32_16x16x32_bf16 v[118:121], v[114:117], v[166:169], v[118:121]
	v_mfma_f32_16x16x32_bf16 v[98:101], v[90:93], v[178:181], v[98:101]
	v_mfma_f32_16x16x32_bf16 v[94:97], v[114:117], v[178:181], v[94:97]
	v_mfma_f32_16x16x32_bf16 v[78:81], v[90:93], v[182:185], v[78:81]
	v_mfma_f32_16x16x32_bf16 v[74:77], v[114:117], v[182:185], v[74:77]
	v_mfma_f32_16x16x32_bf16 v[146:149], v[102:105], v[170:173], v[146:149]
	v_mfma_f32_16x16x32_bf16 v[142:145], v[126:129], v[170:173], v[142:145]
	v_mfma_f32_16x16x32_bf16 v[122:125], v[102:105], v[174:177], v[122:125]
	v_mfma_f32_16x16x32_bf16 v[118:121], v[126:129], v[174:177], v[118:121]
	v_mfma_f32_16x16x32_bf16 v[98:101], v[102:105], v[204:207], v[98:101]
	v_mfma_f32_16x16x32_bf16 v[94:97], v[126:129], v[204:207], v[94:97]
	v_mfma_f32_16x16x32_bf16 v[78:81], v[102:105], v[226:229], v[78:81]
	v_mfma_f32_16x16x32_bf16 v[74:77], v[126:129], v[226:229], v[74:77]
	s_setprio 0
	s_setprio 1
	v_mfma_f32_16x16x32_bf16 v[134:137], v[138:141], v[162:165], v[134:137]
	v_mfma_f32_16x16x32_bf16 v[130:133], v[154:157], v[162:165], v[130:133]
	v_mfma_f32_16x16x32_bf16 v[110:113], v[138:141], v[166:169], v[110:113]
	v_mfma_f32_16x16x32_bf16 v[106:109], v[154:157], v[166:169], v[106:109]
	v_mfma_f32_16x16x32_bf16 v[86:89], v[138:141], v[178:181], v[86:89]
	v_mfma_f32_16x16x32_bf16 v[82:85], v[154:157], v[178:181], v[82:85]
	v_mfma_f32_16x16x32_bf16 v[70:73], v[138:141], v[182:185], v[70:73]
	v_mfma_f32_16x16x32_bf16 v[66:69], v[154:157], v[182:185], v[66:69]
	v_mfma_f32_16x16x32_bf16 v[134:137], v[150:153], v[170:173], v[134:137]
	v_mfma_f32_16x16x32_bf16 v[130:133], v[158:161], v[170:173], v[130:133]
	v_mfma_f32_16x16x32_bf16 v[110:113], v[150:153], v[174:177], v[110:113]
	v_mfma_f32_16x16x32_bf16 v[106:109], v[158:161], v[174:177], v[106:109]
	v_mfma_f32_16x16x32_bf16 v[86:89], v[150:153], v[204:207], v[86:89]
	v_mfma_f32_16x16x32_bf16 v[82:85], v[158:161], v[204:207], v[82:85]
	v_mfma_f32_16x16x32_bf16 v[70:73], v[150:153], v[226:229], v[70:73]
	v_mfma_f32_16x16x32_bf16 v[66:69], v[158:161], v[226:229], v[66:69]
	s_setprio 0
	s_barrier
	s_add_i32 s58, s53, s40
	s_mov_b32 m0, s58
	ds_read_b128 v[162:165], v219 offset:16384
	ds_read_b128 v[166:169], v219 offset:18432
	ds_read_b128 v[170:173], v220 offset:16384
	ds_read_b128 v[174:177], v220 offset:18432
	ds_read_b128 v[178:181], v219 offset:20480
	ds_read_b128 v[182:185], v219 offset:22528
	ds_read_b128 v[204:207], v220 offset:20480
	ds_read_b128 v[226:229], v220 offset:22528
	global_load_lds_dwordx4 v188, s[26:27]
	s_add_i32 m0, s58, 0x2000
	s_add_u32 s58, s26, 0x40000
	s_addc_u32 s59, s27, 0
	s_add_i32 s60, s54, s40
	global_load_lds_dwordx4 v192, s[26:27]
	s_mov_b32 m0, s60
	s_mov_b64 s[98:99], s[28:29]
	global_load_lds_dwordx4 v188, s[58:59]
	s_add_i32 m0, s60, 0x2000
	s_nop 0
	global_load_lds_dwordx4 v192, s[58:59]
	s_mov_b32 m0, s41
	s_nop 0
	global_load_lds_dwordx4 v186, s[28:29]
	s_mov_b32 m0, s42
	s_nop 0
	global_load_lds_dwordx4 v190, s[28:29]
	s_waitcnt vmcnt(8)
	s_waitcnt lgkmcnt(0)
	s_barrier
	s_setprio 1
	s_waitcnt lgkmcnt(0)
	v_mfma_f32_16x16x32_bf16 v[62:65], v[90:93], v[162:165], v[62:65]
	v_mfma_f32_16x16x32_bf16 v[58:61], v[114:117], v[162:165], v[58:61]
	v_mfma_f32_16x16x32_bf16 v[46:49], v[90:93], v[166:169], v[46:49]
	v_mfma_f32_16x16x32_bf16 v[42:45], v[114:117], v[166:169], v[42:45]
	v_mfma_f32_16x16x32_bf16 v[30:33], v[90:93], v[178:181], v[30:33]
	v_mfma_f32_16x16x32_bf16 v[26:29], v[114:117], v[178:181], v[26:29]
	v_mfma_f32_16x16x32_bf16 v[14:17], v[90:93], v[182:185], v[14:17]
	v_mfma_f32_16x16x32_bf16 v[10:13], v[114:117], v[182:185], v[10:13]
	v_mfma_f32_16x16x32_bf16 v[62:65], v[102:105], v[170:173], v[62:65]
	v_mfma_f32_16x16x32_bf16 v[58:61], v[126:129], v[170:173], v[58:61]
	v_mfma_f32_16x16x32_bf16 v[46:49], v[102:105], v[174:177], v[46:49]
	v_mfma_f32_16x16x32_bf16 v[42:45], v[126:129], v[174:177], v[42:45]
	v_mfma_f32_16x16x32_bf16 v[30:33], v[102:105], v[204:207], v[30:33]
	v_mfma_f32_16x16x32_bf16 v[26:29], v[126:129], v[204:207], v[26:29]
	v_mfma_f32_16x16x32_bf16 v[14:17], v[102:105], v[226:229], v[14:17]
	v_mfma_f32_16x16x32_bf16 v[10:13], v[126:129], v[226:229], v[10:13]
	s_setprio 0
	s_setprio 1
	v_mfma_f32_16x16x32_bf16 v[54:57], v[138:141], v[162:165], v[54:57]
	v_mfma_f32_16x16x32_bf16 v[50:53], v[154:157], v[162:165], v[50:53]
	v_mfma_f32_16x16x32_bf16 v[38:41], v[138:141], v[166:169], v[38:41]
	v_mfma_f32_16x16x32_bf16 v[34:37], v[154:157], v[166:169], v[34:37]
	v_mfma_f32_16x16x32_bf16 v[22:25], v[138:141], v[178:181], v[22:25]
	v_mfma_f32_16x16x32_bf16 v[18:21], v[154:157], v[178:181], v[18:21]
	v_mfma_f32_16x16x32_bf16 v[6:9], v[138:141], v[182:185], v[6:9]
	v_mfma_f32_16x16x32_bf16 v[2:5], v[154:157], v[182:185], v[2:5]
	v_mfma_f32_16x16x32_bf16 v[54:57], v[150:153], v[170:173], v[54:57]
	v_mfma_f32_16x16x32_bf16 v[50:53], v[158:161], v[170:173], v[50:53]
	v_mfma_f32_16x16x32_bf16 v[38:41], v[150:153], v[174:177], v[38:41]
	v_mfma_f32_16x16x32_bf16 v[34:37], v[158:161], v[174:177], v[34:37]
	v_mfma_f32_16x16x32_bf16 v[22:25], v[150:153], v[204:207], v[22:25]
	v_mfma_f32_16x16x32_bf16 v[18:21], v[158:161], v[204:207], v[18:21]
	v_mfma_f32_16x16x32_bf16 v[6:9], v[150:153], v[226:229], v[6:9]
	v_mfma_f32_16x16x32_bf16 v[2:5], v[158:161], v[226:229], v[2:5]
	s_setprio 0
	s_barrier
	s_add_i32 s58, 0, 0x18000
	s_add_i32 s59, 0, 0x1c000
	ds_read_b128 v[90:93], v245 offset:32768
	ds_read_b128 v[102:105], v246 offset:32768
	ds_read_b128 v[114:117], v221
	ds_read_b128 v[126:129], v222
	ds_read_b128 v[138:141], v245 offset:49152
	ds_read_b128 v[150:153], v246 offset:49152
	ds_read_b128 v[154:157], v223
	ds_read_b128 v[158:161], v224
	s_add_u32 s28, s28, 0x40000
	s_addc_u32 s29, s29, 0
	s_mov_b32 m0, s43
	ds_read_b128 v[162:165], v219 offset:32768
	ds_read_b128 v[166:169], v219 offset:34816
	ds_read_b128 v[170:173], v220 offset:32768
	ds_read_b128 v[174:177], v220 offset:34816
	ds_read_b128 v[178:181], v219 offset:36864
	ds_read_b128 v[182:185], v219 offset:38912
	ds_read_b128 v[204:207], v220 offset:36864
	ds_read_b128 v[226:229], v220 offset:38912
	global_load_lds_dwordx4 v186, s[28:29]
	s_mov_b32 m0, s44
	s_nop 0
	global_load_lds_dwordx4 v190, s[28:29]
	s_waitcnt vmcnt(8)
	s_waitcnt lgkmcnt(0)
	s_barrier
	s_setprio 1
	s_waitcnt lgkmcnt(0)
	v_mfma_f32_16x16x32_bf16 v[146:149], v[90:93], v[162:165], v[146:149]
	v_mfma_f32_16x16x32_bf16 v[142:145], v[114:117], v[162:165], v[142:145]
	v_mfma_f32_16x16x32_bf16 v[122:125], v[90:93], v[166:169], v[122:125]
	v_mfma_f32_16x16x32_bf16 v[118:121], v[114:117], v[166:169], v[118:121]
	v_mfma_f32_16x16x32_bf16 v[98:101], v[90:93], v[178:181], v[98:101]
	v_mfma_f32_16x16x32_bf16 v[94:97], v[114:117], v[178:181], v[94:97]
	v_mfma_f32_16x16x32_bf16 v[78:81], v[90:93], v[182:185], v[78:81]
	v_mfma_f32_16x16x32_bf16 v[74:77], v[114:117], v[182:185], v[74:77]
	v_mfma_f32_16x16x32_bf16 v[146:149], v[102:105], v[170:173], v[146:149]
	v_mfma_f32_16x16x32_bf16 v[142:145], v[126:129], v[170:173], v[142:145]
	v_mfma_f32_16x16x32_bf16 v[122:125], v[102:105], v[174:177], v[122:125]
	v_mfma_f32_16x16x32_bf16 v[118:121], v[126:129], v[174:177], v[118:121]
	v_mfma_f32_16x16x32_bf16 v[98:101], v[102:105], v[204:207], v[98:101]
	v_mfma_f32_16x16x32_bf16 v[94:97], v[126:129], v[204:207], v[94:97]
	v_mfma_f32_16x16x32_bf16 v[78:81], v[102:105], v[226:229], v[78:81]
	v_mfma_f32_16x16x32_bf16 v[74:77], v[126:129], v[226:229], v[74:77]
	s_setprio 0
	s_setprio 1
	v_mfma_f32_16x16x32_bf16 v[134:137], v[138:141], v[162:165], v[134:137]
	v_mfma_f32_16x16x32_bf16 v[130:133], v[154:157], v[162:165], v[130:133]
	v_mfma_f32_16x16x32_bf16 v[110:113], v[138:141], v[166:169], v[110:113]
	v_mfma_f32_16x16x32_bf16 v[106:109], v[154:157], v[166:169], v[106:109]
	v_mfma_f32_16x16x32_bf16 v[86:89], v[138:141], v[178:181], v[86:89]
	v_mfma_f32_16x16x32_bf16 v[82:85], v[154:157], v[178:181], v[82:85]
	v_mfma_f32_16x16x32_bf16 v[70:73], v[138:141], v[182:185], v[70:73]
	v_mfma_f32_16x16x32_bf16 v[66:69], v[154:157], v[182:185], v[66:69]
	v_mfma_f32_16x16x32_bf16 v[134:137], v[150:153], v[170:173], v[134:137]
	v_mfma_f32_16x16x32_bf16 v[130:133], v[158:161], v[170:173], v[130:133]
	v_mfma_f32_16x16x32_bf16 v[110:113], v[150:153], v[174:177], v[110:113]
	v_mfma_f32_16x16x32_bf16 v[106:109], v[158:161], v[174:177], v[106:109]
	v_mfma_f32_16x16x32_bf16 v[86:89], v[150:153], v[204:207], v[86:89]
	v_mfma_f32_16x16x32_bf16 v[82:85], v[158:161], v[204:207], v[82:85]
	v_mfma_f32_16x16x32_bf16 v[70:73], v[150:153], v[226:229], v[70:73]
	v_mfma_f32_16x16x32_bf16 v[66:69], v[158:161], v[226:229], v[66:69]
	s_setprio 0
	s_barrier
	s_add_i32 s28, s58, s40
	s_add_i32 m0, s28, 0xffffff80
	ds_read_b128 v[162:165], v219 offset:49152
	ds_read_b128 v[166:169], v219 offset:51200
	ds_read_b128 v[170:173], v220 offset:49152
	ds_read_b128 v[174:177], v220 offset:51200
	ds_read_b128 v[178:181], v219 offset:53248
	ds_read_b128 v[182:185], v219 offset:55296
	ds_read_b128 v[204:207], v220 offset:53248
	ds_read_b128 v[226:229], v220 offset:55296
	global_load_lds_dwordx4 v188, s[26:27] offset:128
	s_add_i32 m0, s28, 0x1f80
	s_add_i32 s28, s59, s40
	global_load_lds_dwordx4 v192, s[26:27] offset:128
	s_add_u32 s26, s26, 0x40080
	s_addc_u32 s27, s27, 0
	s_mov_b32 m0, s28
	s_nop 0
	global_load_lds_dwordx4 v188, s[26:27]
	s_add_i32 m0, s28, 0x2000
	s_nop 0
	global_load_lds_dwordx4 v192, s[26:27]
	s_add_i32 m0, s48, 0xffffff80
	s_nop 0
	global_load_lds_dwordx4 v186, s[98:99] offset:128
	s_add_i32 m0, s49, 0xffffff80
	s_nop 0
	global_load_lds_dwordx4 v190, s[98:99] offset:128
	s_waitcnt vmcnt(8)
	s_waitcnt lgkmcnt(0)
	s_barrier
	s_setprio 1
	s_waitcnt lgkmcnt(0)
	v_mfma_f32_16x16x32_bf16 v[62:65], v[90:93], v[162:165], v[62:65]
	v_mfma_f32_16x16x32_bf16 v[58:61], v[114:117], v[162:165], v[58:61]
	v_mfma_f32_16x16x32_bf16 v[46:49], v[90:93], v[166:169], v[46:49]
	v_mfma_f32_16x16x32_bf16 v[42:45], v[114:117], v[166:169], v[42:45]
	v_mfma_f32_16x16x32_bf16 v[30:33], v[90:93], v[178:181], v[30:33]
	v_mfma_f32_16x16x32_bf16 v[26:29], v[114:117], v[178:181], v[26:29]
	v_mfma_f32_16x16x32_bf16 v[14:17], v[90:93], v[182:185], v[14:17]
	v_mfma_f32_16x16x32_bf16 v[10:13], v[114:117], v[182:185], v[10:13]
	v_mfma_f32_16x16x32_bf16 v[62:65], v[102:105], v[170:173], v[62:65]
	v_mfma_f32_16x16x32_bf16 v[58:61], v[126:129], v[170:173], v[58:61]
	v_mfma_f32_16x16x32_bf16 v[46:49], v[102:105], v[174:177], v[46:49]
	v_mfma_f32_16x16x32_bf16 v[42:45], v[126:129], v[174:177], v[42:45]
	v_mfma_f32_16x16x32_bf16 v[30:33], v[102:105], v[204:207], v[30:33]
	v_mfma_f32_16x16x32_bf16 v[26:29], v[126:129], v[204:207], v[26:29]
	v_mfma_f32_16x16x32_bf16 v[14:17], v[102:105], v[226:229], v[14:17]
	v_mfma_f32_16x16x32_bf16 v[10:13], v[126:129], v[226:229], v[10:13]
	s_setprio 0
	s_setprio 1
	v_mfma_f32_16x16x32_bf16 v[54:57], v[138:141], v[162:165], v[54:57]
	v_mfma_f32_16x16x32_bf16 v[50:53], v[154:157], v[162:165], v[50:53]
	v_mfma_f32_16x16x32_bf16 v[38:41], v[138:141], v[166:169], v[38:41]
	v_mfma_f32_16x16x32_bf16 v[34:37], v[154:157], v[166:169], v[34:37]
	v_mfma_f32_16x16x32_bf16 v[22:25], v[138:141], v[178:181], v[22:25]
	v_mfma_f32_16x16x32_bf16 v[18:21], v[154:157], v[178:181], v[18:21]
	v_mfma_f32_16x16x32_bf16 v[6:9], v[138:141], v[182:185], v[6:9]
	v_mfma_f32_16x16x32_bf16 v[2:5], v[154:157], v[182:185], v[2:5]
	v_mfma_f32_16x16x32_bf16 v[54:57], v[150:153], v[170:173], v[54:57]
	v_mfma_f32_16x16x32_bf16 v[50:53], v[158:161], v[170:173], v[50:53]
	v_mfma_f32_16x16x32_bf16 v[38:41], v[150:153], v[174:177], v[38:41]
	v_mfma_f32_16x16x32_bf16 v[34:37], v[158:161], v[174:177], v[34:37]
	v_mfma_f32_16x16x32_bf16 v[22:25], v[150:153], v[204:207], v[22:25]
	v_mfma_f32_16x16x32_bf16 v[18:21], v[158:161], v[204:207], v[18:21]
	v_mfma_f32_16x16x32_bf16 v[6:9], v[150:153], v[226:229], v[6:9]
	v_mfma_f32_16x16x32_bf16 v[2:5], v[158:161], v[226:229], v[2:5]
	s_setprio 0
	s_barrier
	s_add_i32 s57, s57, 2
	s_add_u32 s24, s24, 0x100
	s_addc_u32 s25, s25, 0
	s_add_u32 s55, s55, 0x100
	s_addc_u32 s56, s56, 0
	s_cmp_gt_u32 s57, 13
	s_cbranch_scc0 .LBB0_1629
	s_branch .Lpx_4
.Lpeel_4:
	s_mov_b32 s100, 0
	ds_read_b128 v[90:93], v211
	ds_read_b128 v[102:105], v212
	ds_read_b128 v[114:117], v213
	ds_read_b128 v[126:129], v214
	ds_read_b128 v[138:141], v215
	ds_read_b128 v[150:153], v216
	ds_read_b128 v[154:157], v217
	ds_read_b128 v[158:161], v218
	s_add_u32 s26, s24, 0xfffc0080
	s_addc_u32 s27, s25, -1
	s_cmp_eq_u32 s57, 12
	s_cselect_b32 s29, s15, s27
	s_cselect_b32 s28, s21, s26
	s_cselect_b32 s27, s13, s56
	s_cselect_b32 s26, s23, s55
	s_add_i32 m0, s41, 0xc000
	ds_read_b128 v[162:165], v219
	ds_read_b128 v[166:169], v219 offset:2048
	ds_read_b128 v[170:173], v220
	ds_read_b128 v[174:177], v220 offset:2048
	ds_read_b128 v[178:181], v219 offset:4096
	ds_read_b128 v[182:185], v219 offset:6144
	ds_read_b128 v[204:207], v220 offset:4096
	ds_read_b128 v[226:229], v220 offset:6144
	global_load_lds_dwordx4 v196, s[24:25]
	s_add_i32 m0, s41, 0xe000
	s_nop 0
	global_load_lds_dwordx4 v198, s[24:25]
	s_waitcnt vmcnt(8)
	s_waitcnt lgkmcnt(0)
	s_barrier
	s_setprio 1
	s_waitcnt lgkmcnt(0)
	v_mfma_f32_16x16x32_bf16 v[146:149], v[90:93], v[162:165], 0
	v_mfma_f32_16x16x32_bf16 v[142:145], v[114:117], v[162:165], 0
	v_mfma_f32_16x16x32_bf16 v[122:125], v[90:93], v[166:169], 0
	v_mfma_f32_16x16x32_bf16 v[118:121], v[114:117], v[166:169], 0
	v_mfma_f32_16x16x32_bf16 v[98:101], v[90:93], v[178:181], 0
	v_mfma_f32_16x16x32_bf16 v[94:97], v[114:117], v[178:181], 0
	v_mfma_f32_16x16x32_bf16 v[78:81], v[90:93], v[182:185], 0
	v_mfma_f32_16x16x32_bf16 v[74:77], v[114:117], v[182:185], 0
	v_mfma_f32_16x16x32_bf16 v[146:149], v[102:105], v[170:173], v[146:149]
	v_mfma_f32_16x16x32_bf16 v[142:145], v[126:129], v[170:173], v[142:145]
	v_mfma_f32_16x16x32_bf16 v[122:125], v[102:105], v[174:177], v[122:125]
	v_mfma_f32_16x16x32_bf16 v[118:121], v[126:129], v[174:177], v[118:121]
	v_mfma_f32_16x16x32_bf16 v[98:101], v[102:105], v[204:207], v[98:101]
	v_mfma_f32_16x16x32_bf16 v[94:97], v[126:129], v[204:207], v[94:97]
	v_mfma_f32_16x16x32_bf16 v[78:81], v[102:105], v[226:229], v[78:81]
	v_mfma_f32_16x16x32_bf16 v[74:77], v[126:129], v[226:229], v[74:77]
	s_setprio 0
	s_setprio 1
	v_mfma_f32_16x16x32_bf16 v[134:137], v[138:141], v[162:165], 0
	v_mfma_f32_16x16x32_bf16 v[130:133], v[154:157], v[162:165], 0
	v_mfma_f32_16x16x32_bf16 v[110:113], v[138:141], v[166:169], 0
	v_mfma_f32_16x16x32_bf16 v[106:109], v[154:157], v[166:169], 0
	v_mfma_f32_16x16x32_bf16 v[86:89], v[138:141], v[178:181], 0
	v_mfma_f32_16x16x32_bf16 v[82:85], v[154:157], v[178:181], 0
	v_mfma_f32_16x16x32_bf16 v[70:73], v[138:141], v[182:185], 0
	v_mfma_f32_16x16x32_bf16 v[66:69], v[154:157], v[182:185], 0
	v_mfma_f32_16x16x32_bf16 v[134:137], v[150:153], v[170:173], v[134:137]
	v_mfma_f32_16x16x32_bf16 v[130:133], v[158:161], v[170:173], v[130:133]
	v_mfma_f32_16x16x32_bf16 v[110:113], v[150:153], v[174:177], v[110:113]
	v_mfma_f32_16x16x32_bf16 v[106:109], v[158:161], v[174:177], v[106:109]
	v_mfma_f32_16x16x32_bf16 v[86:89], v[150:153], v[204:207], v[86:89]
	v_mfma_f32_16x16x32_bf16 v[82:85], v[158:161], v[204:207], v[82:85]
	v_mfma_f32_16x16x32_bf16 v[70:73], v[150:153], v[226:229], v[70:73]
	v_mfma_f32_16x16x32_bf16 v[66:69], v[158:161], v[226:229], v[66:69]
	s_setprio 0
	s_barrier
	s_add_i32 s58, s53, s40
	s_mov_b32 m0, s58
	ds_read_b128 v[162:165], v219 offset:16384
	ds_read_b128 v[166:169], v219 offset:18432
	ds_read_b128 v[170:173], v220 offset:16384
	ds_read_b128 v[174:177], v220 offset:18432
	ds_read_b128 v[178:181], v219 offset:20480
	ds_read_b128 v[182:185], v219 offset:22528
	ds_read_b128 v[204:207], v220 offset:20480
	ds_read_b128 v[226:229], v220 offset:22528
	global_load_lds_dwordx4 v188, s[26:27]
	s_add_i32 m0, s58, 0x2000
	s_add_u32 s58, s26, 0x40000
	s_addc_u32 s59, s27, 0
	s_add_i32 s60, s54, s40
	global_load_lds_dwordx4 v192, s[26:27]
	s_mov_b32 m0, s60
	s_mov_b64 s[98:99], s[28:29]
	global_load_lds_dwordx4 v188, s[58:59]
	s_add_i32 m0, s60, 0x2000
	s_nop 0
	global_load_lds_dwordx4 v192, s[58:59]
	s_mov_b32 m0, s41
	s_nop 0
	global_load_lds_dwordx4 v186, s[28:29]
	s_mov_b32 m0, s42
	s_nop 0
	global_load_lds_dwordx4 v190, s[28:29]
	s_waitcnt vmcnt(8)
	s_waitcnt lgkmcnt(0)
	s_barrier
	s_setprio 1
	s_waitcnt lgkmcnt(0)
	v_mfma_f32_16x16x32_bf16 v[62:65], v[90:93], v[162:165], 0
	v_mfma_f32_16x16x32_bf16 v[58:61], v[114:117], v[162:165], 0
	v_mfma_f32_16x16x32_bf16 v[46:49], v[90:93], v[166:169], 0
	v_mfma_f32_16x16x32_bf16 v[42:45], v[114:117], v[166:169], 0
	v_mfma_f32_16x16x32_bf16 v[30:33], v[90:93], v[178:181], 0
	v_mfma_f32_16x16x32_bf16 v[26:29], v[114:117], v[178:181], 0
	v_mfma_f32_16x16x32_bf16 v[14:17], v[90:93], v[182:185], 0
	v_mfma_f32_16x16x32_bf16 v[10:13], v[114:117], v[182:185], 0
	v_mfma_f32_16x16x32_bf16 v[62:65], v[102:105], v[170:173], v[62:65]
	v_mfma_f32_16x16x32_bf16 v[58:61], v[126:129], v[170:173], v[58:61]
	v_mfma_f32_16x16x32_bf16 v[46:49], v[102:105], v[174:177], v[46:49]
	v_mfma_f32_16x16x32_bf16 v[42:45], v[126:129], v[174:177], v[42:45]
	v_mfma_f32_16x16x32_bf16 v[30:33], v[102:105], v[204:207], v[30:33]
	v_mfma_f32_16x16x32_bf16 v[26:29], v[126:129], v[204:207], v[26:29]
	v_mfma_f32_16x16x32_bf16 v[14:17], v[102:105], v[226:229], v[14:17]
	v_mfma_f32_16x16x32_bf16 v[10:13], v[126:129], v[226:229], v[10:13]
	s_setprio 0
	s_setprio 1
	v_mfma_f32_16x16x32_bf16 v[54:57], v[138:141], v[162:165], 0
	v_mfma_f32_16x16x32_bf16 v[50:53], v[154:157], v[162:165], 0
	v_mfma_f32_16x16x32_bf16 v[38:41], v[138:141], v[166:169], 0
	v_mfma_f32_16x16x32_bf16 v[34:37], v[154:157], v[166:169], 0
	v_mfma_f32_16x16x32_bf16 v[22:25], v[138:141], v[178:181], 0
	v_mfma_f32_16x16x32_bf16 v[18:21], v[154:157], v[178:181], 0
	v_mfma_f32_16x16x32_bf16 v[6:9], v[138:141], v[182:185], 0
	v_mfma_f32_16x16x32_bf16 v[2:5], v[154:157], v[182:185], 0
	v_mfma_f32_16x16x32_bf16 v[54:57], v[150:153], v[170:173], v[54:57]
	v_mfma_f32_16x16x32_bf16 v[50:53], v[158:161], v[170:173], v[50:53]
	v_mfma_f32_16x16x32_bf16 v[38:41], v[150:153], v[174:177], v[38:41]
	v_mfma_f32_16x16x32_bf16 v[34:37], v[158:161], v[174:177], v[34:37]
	v_mfma_f32_16x16x32_bf16 v[22:25], v[150:153], v[204:207], v[22:25]
	v_mfma_f32_16x16x32_bf16 v[18:21], v[158:161], v[204:207], v[18:21]
	v_mfma_f32_16x16x32_bf16 v[6:9], v[150:153], v[226:229], v[6:9]
	v_mfma_f32_16x16x32_bf16 v[2:5], v[158:161], v[226:229], v[2:5]
	s_setprio 0
	s_barrier
	s_add_i32 s58, 0, 0x18000
	s_add_i32 s59, 0, 0x1c000
	ds_read_b128 v[90:93], v245 offset:32768
	ds_read_b128 v[102:105], v246 offset:32768
	ds_read_b128 v[114:117], v221
	ds_read_b128 v[126:129], v222
	ds_read_b128 v[138:141], v245 offset:49152
	ds_read_b128 v[150:153], v246 offset:49152
	ds_read_b128 v[154:157], v223
	ds_read_b128 v[158:161], v224
	s_add_u32 s28, s28, 0x40000
	s_addc_u32 s29, s29, 0
	s_mov_b32 m0, s43
	ds_read_b128 v[162:165], v219 offset:32768
	ds_read_b128 v[166:169], v219 offset:34816
	ds_read_b128 v[170:173], v220 offset:32768
	ds_read_b128 v[174:177], v220 offset:34816
	ds_read_b128 v[178:181], v219 offset:36864
	ds_read_b128 v[182:185], v219 offset:38912
	ds_read_b128 v[204:207], v220 offset:36864
	ds_read_b128 v[226:229], v220 offset:38912
	global_load_lds_dwordx4 v186, s[28:29]
	s_mov_b32 m0, s44
	s_nop 0
	global_load_lds_dwordx4 v190, s[28:29]
	s_waitcnt vmcnt(8)
	s_waitcnt lgkmcnt(0)
	s_barrier
	s_setprio 1
	s_waitcnt lgkmcnt(0)
	v_mfma_f32_16x16x32_bf16 v[146:149], v[90:93], v[162:165], v[146:149]
	v_mfma_f32_16x16x32_bf16 v[142:145], v[114:117], v[162:165], v[142:145]
	v_mfma_f32_16x16x32_bf16 v[122:125], v[90:93], v[166:169], v[122:125]
	v_mfma_f32_16x16x32_bf16 v[118:121], v[114:117], v[166:169], v[118:121]
	v_mfma_f32_16x16x32_bf16 v[98:101], v[90:93], v[178:181], v[98:101]
	v_mfma_f32_16x16x32_bf16 v[94:97], v[114:117], v[178:181], v[94:97]
	v_mfma_f32_16x16x32_bf16 v[78:81], v[90:93], v[182:185], v[78:81]
	v_mfma_f32_16x16x32_bf16 v[74:77], v[114:117], v[182:185], v[74:77]
	v_mfma_f32_16x16x32_bf16 v[146:149], v[102:105], v[170:173], v[146:149]
	v_mfma_f32_16x16x32_bf16 v[142:145], v[126:129], v[170:173], v[142:145]
	v_mfma_f32_16x16x32_bf16 v[122:125], v[102:105], v[174:177], v[122:125]
	v_mfma_f32_16x16x32_bf16 v[118:121], v[126:129], v[174:177], v[118:121]
	v_mfma_f32_16x16x32_bf16 v[98:101], v[102:105], v[204:207], v[98:101]
	v_mfma_f32_16x16x32_bf16 v[94:97], v[126:129], v[204:207], v[94:97]
	v_mfma_f32_16x16x32_bf16 v[78:81], v[102:105], v[226:229], v[78:81]
	v_mfma_f32_16x16x32_bf16 v[74:77], v[126:129], v[226:229], v[74:77]
	s_setprio 0
	s_setprio 1
	v_mfma_f32_16x16x32_bf16 v[134:137], v[138:141], v[162:165], v[134:137]
	v_mfma_f32_16x16x32_bf16 v[130:133], v[154:157], v[162:165], v[130:133]
	v_mfma_f32_16x16x32_bf16 v[110:113], v[138:141], v[166:169], v[110:113]
	v_mfma_f32_16x16x32_bf16 v[106:109], v[154:157], v[166:169], v[106:109]
	v_mfma_f32_16x16x32_bf16 v[86:89], v[138:141], v[178:181], v[86:89]
	v_mfma_f32_16x16x32_bf16 v[82:85], v[154:157], v[178:181], v[82:85]
	v_mfma_f32_16x16x32_bf16 v[70:73], v[138:141], v[182:185], v[70:73]
	v_mfma_f32_16x16x32_bf16 v[66:69], v[154:157], v[182:185], v[66:69]
	v_mfma_f32_16x16x32_bf16 v[134:137], v[150:153], v[170:173], v[134:137]
	v_mfma_f32_16x16x32_bf16 v[130:133], v[158:161], v[170:173], v[130:133]
	v_mfma_f32_16x16x32_bf16 v[110:113], v[150:153], v[174:177], v[110:113]
	v_mfma_f32_16x16x32_bf16 v[106:109], v[158:161], v[174:177], v[106:109]
	v_mfma_f32_16x16x32_bf16 v[86:89], v[150:153], v[204:207], v[86:89]
	v_mfma_f32_16x16x32_bf16 v[82:85], v[158:161], v[204:207], v[82:85]
	v_mfma_f32_16x16x32_bf16 v[70:73], v[150:153], v[226:229], v[70:73]
	v_mfma_f32_16x16x32_bf16 v[66:69], v[158:161], v[226:229], v[66:69]
	s_setprio 0
	s_barrier
	s_add_i32 s28, s58, s40
	s_add_i32 m0, s28, 0xffffff80
	ds_read_b128 v[162:165], v219 offset:49152
	ds_read_b128 v[166:169], v219 offset:51200
	ds_read_b128 v[170:173], v220 offset:49152
	ds_read_b128 v[174:177], v220 offset:51200
	ds_read_b128 v[178:181], v219 offset:53248
	ds_read_b128 v[182:185], v219 offset:55296
	ds_read_b128 v[204:207], v220 offset:53248
	ds_read_b128 v[226:229], v220 offset:55296
	global_load_lds_dwordx4 v188, s[26:27] offset:128
	s_add_i32 m0, s28, 0x1f80
	s_add_i32 s28, s59, s40
	global_load_lds_dwordx4 v192, s[26:27] offset:128
	s_add_u32 s26, s26, 0x40080
	s_addc_u32 s27, s27, 0
	s_mov_b32 m0, s28
	s_nop 0
	global_load_lds_dwordx4 v188, s[26:27]
	s_add_i32 m0, s28, 0x2000
	s_nop 0
	global_load_lds_dwordx4 v192, s[26:27]
	s_add_i32 m0, s48, 0xffffff80
	s_nop 0
	global_load_lds_dwordx4 v186, s[98:99] offset:128
	s_add_i32 m0, s49, 0xffffff80
	s_nop 0
	global_load_lds_dwordx4 v190, s[98:99] offset:128
	s_waitcnt vmcnt(8)
	s_waitcnt lgkmcnt(0)
	s_barrier
	s_setprio 1
	s_waitcnt lgkmcnt(0)
	v_mfma_f32_16x16x32_bf16 v[62:65], v[90:93], v[162:165], v[62:65]
	v_mfma_f32_16x16x32_bf16 v[58:61], v[114:117], v[162:165], v[58:61]
	v_mfma_f32_16x16x32_bf16 v[46:49], v[90:93], v[166:169], v[46:49]
	v_mfma_f32_16x16x32_bf16 v[42:45], v[114:117], v[166:169], v[42:45]
	v_mfma_f32_16x16x32_bf16 v[30:33], v[90:93], v[178:181], v[30:33]
	v_mfma_f32_16x16x32_bf16 v[26:29], v[114:117], v[178:181], v[26:29]
	v_mfma_f32_16x16x32_bf16 v[14:17], v[90:93], v[182:185], v[14:17]
	v_mfma_f32_16x16x32_bf16 v[10:13], v[114:117], v[182:185], v[10:13]
	v_mfma_f32_16x16x32_bf16 v[62:65], v[102:105], v[170:173], v[62:65]
	v_mfma_f32_16x16x32_bf16 v[58:61], v[126:129], v[170:173], v[58:61]
	v_mfma_f32_16x16x32_bf16 v[46:49], v[102:105], v[174:177], v[46:49]
	v_mfma_f32_16x16x32_bf16 v[42:45], v[126:129], v[174:177], v[42:45]
	v_mfma_f32_16x16x32_bf16 v[30:33], v[102:105], v[204:207], v[30:33]
	v_mfma_f32_16x16x32_bf16 v[26:29], v[126:129], v[204:207], v[26:29]
	v_mfma_f32_16x16x32_bf16 v[14:17], v[102:105], v[226:229], v[14:17]
	v_mfma_f32_16x16x32_bf16 v[10:13], v[126:129], v[226:229], v[10:13]
	s_setprio 0
	s_setprio 1
	v_mfma_f32_16x16x32_bf16 v[54:57], v[138:141], v[162:165], v[54:57]
	v_mfma_f32_16x16x32_bf16 v[50:53], v[154:157], v[162:165], v[50:53]
	v_mfma_f32_16x16x32_bf16 v[38:41], v[138:141], v[166:169], v[38:41]
	v_mfma_f32_16x16x32_bf16 v[34:37], v[154:157], v[166:169], v[34:37]
	v_mfma_f32_16x16x32_bf16 v[22:25], v[138:141], v[178:181], v[22:25]
	v_mfma_f32_16x16x32_bf16 v[18:21], v[154:157], v[178:181], v[18:21]
	v_mfma_f32_16x16x32_bf16 v[6:9], v[138:141], v[182:185], v[6:9]
	v_mfma_f32_16x16x32_bf16 v[2:5], v[154:157], v[182:185], v[2:5]
	v_mfma_f32_16x16x32_bf16 v[54:57], v[150:153], v[170:173], v[54:57]
	v_mfma_f32_16x16x32_bf16 v[50:53], v[158:161], v[170:173], v[50:53]
	v_mfma_f32_16x16x32_bf16 v[38:41], v[150:153], v[174:177], v[38:41]
	v_mfma_f32_16x16x32_bf16 v[34:37], v[158:161], v[174:177], v[34:37]
	v_mfma_f32_16x16x32_bf16 v[22:25], v[150:153], v[204:207], v[22:25]
	v_mfma_f32_16x16x32_bf16 v[18:21], v[158:161], v[204:207], v[18:21]
	v_mfma_f32_16x16x32_bf16 v[6:9], v[150:153], v[226:229], v[6:9]
	v_mfma_f32_16x16x32_bf16 v[2:5], v[158:161], v[226:229], v[2:5]
	s_setprio 0
	s_barrier
	s_add_i32 s57, s57, 2
	s_add_u32 s24, s24, 0x100
	s_addc_u32 s25, s25, 0
	s_add_u32 s55, s55, 0x100
	s_addc_u32 s56, s56, 0
	s_cmp_gt_u32 s57, 13
	s_cbranch_scc0 .LBB0_1629

.LBB0_1721:
	s_cmp_lg_u32 s100, 0
	s_cbranch_scc1 .Lpeel_5
	ds_read_b128 v[150:153], v245
	ds_read_b128 v[160:163], v246
	ds_read_b128 v[164:167], v245 offset:2048
	ds_read_b128 v[168:171], v246 offset:2048
	ds_read_b128 v[172:175], v245 offset:16384
	ds_read_b128 v[176:179], v246 offset:16384
	ds_read_b128 v[180:183], v245 offset:18432
	ds_read_b128 v[184:187], v246 offset:18432
	s_add_u32 s26, s22, 0xfffc0080
	s_addc_u32 s27, s23, -1
	s_and_b64 s[24:25], s[24:25], exec
	s_cselect_b32 s27, s13, s27
	s_cselect_b32 s26, s58, s26
	s_cselect_b32 s25, s5, s62
	s_cselect_b32 s24, s59, s61
	s_add_i32 m0, s38, 0xc000
	ds_read_b128 v[188:191], v157
	s_waitcnt lgkmcnt(0)
	ds_read_b128 v[192:195], v157 offset:2048
	ds_read_b128 v[196:199], v158
	ds_read_b128 v[200:203], v158 offset:2048
	ds_read_b128 v[204:207], v157 offset:4096
	ds_read_b128 v[208:211], v157 offset:6144
	ds_read_b128 v[212:215], v158 offset:4096
	ds_read_b128 v[216:219], v158 offset:6144
	global_load_lds_dwordx4 v140, s[22:23]
	s_add_i32 m0, s38, 0xe000
	s_nop 0
	global_load_lds_dwordx4 v142, s[22:23]
	s_waitcnt vmcnt(8)
	s_waitcnt lgkmcnt(0)
	s_barrier
	s_setprio 1
	v_mfma_f32_16x16x32_bf16 v[126:129], v[150:153], v[188:191], v[126:129]
	v_mfma_f32_16x16x32_bf16 v[118:121], v[164:167], v[188:191], v[118:121]
	s_waitcnt lgkmcnt(0)
	v_mfma_f32_16x16x32_bf16 v[110:113], v[150:153], v[192:195], v[110:113]
	v_mfma_f32_16x16x32_bf16 v[102:105], v[164:167], v[192:195], v[102:105]
	v_mfma_f32_16x16x32_bf16 v[94:97], v[150:153], v[204:207], v[94:97]
	v_mfma_f32_16x16x32_bf16 v[86:89], v[164:167], v[204:207], v[86:89]
	v_mfma_f32_16x16x32_bf16 v[78:81], v[150:153], v[208:211], v[78:81]
	v_mfma_f32_16x16x32_bf16 v[70:73], v[164:167], v[208:211], v[70:73]
	v_mfma_f32_16x16x32_bf16 v[126:129], v[160:163], v[196:199], v[126:129]
	v_mfma_f32_16x16x32_bf16 v[118:121], v[168:171], v[196:199], v[118:121]
	v_mfma_f32_16x16x32_bf16 v[110:113], v[160:163], v[200:203], v[110:113]
	v_mfma_f32_16x16x32_bf16 v[102:105], v[168:171], v[200:203], v[102:105]
	v_mfma_f32_16x16x32_bf16 v[94:97], v[160:163], v[212:215], v[94:97]
	v_mfma_f32_16x16x32_bf16 v[86:89], v[168:171], v[212:215], v[86:89]
	v_mfma_f32_16x16x32_bf16 v[78:81], v[160:163], v[216:219], v[78:81]
	v_mfma_f32_16x16x32_bf16 v[70:73], v[168:171], v[216:219], v[70:73]
	s_setprio 0
	s_setprio 1
	v_mfma_f32_16x16x32_bf16 v[122:125], v[172:175], v[188:191], v[122:125]
	v_mfma_f32_16x16x32_bf16 v[114:117], v[180:183], v[188:191], v[114:117]
	v_mfma_f32_16x16x32_bf16 v[106:109], v[172:175], v[192:195], v[106:109]
	v_mfma_f32_16x16x32_bf16 v[98:101], v[180:183], v[192:195], v[98:101]
	v_mfma_f32_16x16x32_bf16 v[90:93], v[172:175], v[204:207], v[90:93]
	v_mfma_f32_16x16x32_bf16 v[82:85], v[180:183], v[204:207], v[82:85]
	v_mfma_f32_16x16x32_bf16 v[74:77], v[172:175], v[208:211], v[74:77]
	v_mfma_f32_16x16x32_bf16 v[66:69], v[180:183], v[208:211], v[66:69]
	v_mfma_f32_16x16x32_bf16 v[122:125], v[176:179], v[196:199], v[122:125]
	v_mfma_f32_16x16x32_bf16 v[114:117], v[184:187], v[196:199], v[114:117]
	v_mfma_f32_16x16x32_bf16 v[106:109], v[176:179], v[200:203], v[106:109]
	v_mfma_f32_16x16x32_bf16 v[98:101], v[184:187], v[200:203], v[98:101]
	v_mfma_f32_16x16x32_bf16 v[90:93], v[176:179], v[212:215], v[90:93]
	v_mfma_f32_16x16x32_bf16 v[82:85], v[184:187], v[212:215], v[82:85]
	v_mfma_f32_16x16x32_bf16 v[74:77], v[176:179], v[216:219], v[74:77]
	v_mfma_f32_16x16x32_bf16 v[66:69], v[184:187], v[216:219], v[66:69]
	s_setprio 0
	s_barrier
	s_add_i32 s64, s49, s21
	s_mov_b32 m0, s64
	ds_read_b128 v[188:191], v157 offset:16384
	ds_read_b128 v[192:195], v157 offset:18432
	ds_read_b128 v[196:199], v158 offset:16384
	ds_read_b128 v[200:203], v158 offset:18432
	ds_read_b128 v[204:207], v157 offset:20480
	ds_read_b128 v[208:211], v157 offset:22528
	ds_read_b128 v[212:215], v158 offset:20480
	ds_read_b128 v[216:219], v158 offset:22528
	global_load_lds_dwordx4 v132, s[24:25]
	s_add_i32 m0, s64, 0x2000
	s_add_u32 s64, s24, 0x40000
	s_addc_u32 s65, s25, 0
	s_add_i32 s66, s51, s21
	global_load_lds_dwordx4 v136, s[24:25]
	s_mov_b32 m0, s66
	s_mov_b64 s[98:99], s[26:27]
	global_load_lds_dwordx4 v132, s[64:65]
	s_add_i32 m0, s66, 0x2000
	s_nop 0
	global_load_lds_dwordx4 v136, s[64:65]
	s_mov_b32 m0, s38
	s_nop 0
	global_load_lds_dwordx4 v130, s[26:27]
	s_mov_b32 m0, s39
	s_nop 0
	global_load_lds_dwordx4 v134, s[26:27]
	s_waitcnt vmcnt(8)
	s_waitcnt lgkmcnt(0)
	s_barrier
	s_setprio 1
	s_waitcnt lgkmcnt(0)
	v_mfma_f32_16x16x32_bf16 v[62:65], v[150:153], v[188:191], v[62:65]
	v_mfma_f32_16x16x32_bf16 v[54:57], v[164:167], v[188:191], v[54:57]
	v_mfma_f32_16x16x32_bf16 v[46:49], v[150:153], v[192:195], v[46:49]
	v_mfma_f32_16x16x32_bf16 v[38:41], v[164:167], v[192:195], v[38:41]
	v_mfma_f32_16x16x32_bf16 v[30:33], v[150:153], v[204:207], v[30:33]
	v_mfma_f32_16x16x32_bf16 v[22:25], v[164:167], v[204:207], v[22:25]
	v_mfma_f32_16x16x32_bf16 v[14:17], v[150:153], v[208:211], v[14:17]
	v_mfma_f32_16x16x32_bf16 v[6:9], v[164:167], v[208:211], v[6:9]
	v_mfma_f32_16x16x32_bf16 v[62:65], v[160:163], v[196:199], v[62:65]
	v_mfma_f32_16x16x32_bf16 v[54:57], v[168:171], v[196:199], v[54:57]
	v_mfma_f32_16x16x32_bf16 v[46:49], v[160:163], v[200:203], v[46:49]
	v_mfma_f32_16x16x32_bf16 v[38:41], v[168:171], v[200:203], v[38:41]
	v_mfma_f32_16x16x32_bf16 v[30:33], v[160:163], v[212:215], v[30:33]
	v_mfma_f32_16x16x32_bf16 v[22:25], v[168:171], v[212:215], v[22:25]
	v_mfma_f32_16x16x32_bf16 v[14:17], v[160:163], v[216:219], v[14:17]
	v_mfma_f32_16x16x32_bf16 v[6:9], v[168:171], v[216:219], v[6:9]
	s_setprio 0
	s_setprio 1
	v_mfma_f32_16x16x32_bf16 v[58:61], v[172:175], v[188:191], v[58:61]
	v_mfma_f32_16x16x32_bf16 v[50:53], v[180:183], v[188:191], v[50:53]
	v_mfma_f32_16x16x32_bf16 v[42:45], v[172:175], v[192:195], v[42:45]
	v_mfma_f32_16x16x32_bf16 v[34:37], v[180:183], v[192:195], v[34:37]
	v_mfma_f32_16x16x32_bf16 v[26:29], v[172:175], v[204:207], v[26:29]
	v_mfma_f32_16x16x32_bf16 v[18:21], v[180:183], v[204:207], v[18:21]
	v_mfma_f32_16x16x32_bf16 v[10:13], v[172:175], v[208:211], v[10:13]
	v_mfma_f32_16x16x32_bf16 v[2:5], v[180:183], v[208:211], v[2:5]
	v_mfma_f32_16x16x32_bf16 v[58:61], v[176:179], v[196:199], v[58:61]
	v_mfma_f32_16x16x32_bf16 v[50:53], v[184:187], v[196:199], v[50:53]
	v_mfma_f32_16x16x32_bf16 v[42:45], v[176:179], v[200:203], v[42:45]
	v_mfma_f32_16x16x32_bf16 v[34:37], v[184:187], v[200:203], v[34:37]
	v_mfma_f32_16x16x32_bf16 v[26:29], v[176:179], v[212:215], v[26:29]
	v_mfma_f32_16x16x32_bf16 v[18:21], v[184:187], v[212:215], v[18:21]
	v_mfma_f32_16x16x32_bf16 v[10:13], v[176:179], v[216:219], v[10:13]
	v_mfma_f32_16x16x32_bf16 v[2:5], v[184:187], v[216:219], v[2:5]
	s_setprio 0
	s_barrier
	s_add_i32 s64, 0, 0x18000
	s_add_i32 s65, 0, 0x1c000
	ds_read_b128 v[150:153], v245 offset:32768
	ds_read_b128 v[160:163], v246 offset:32768
	ds_read_b128 v[164:167], v245 offset:34816
	ds_read_b128 v[168:171], v246 offset:34816
	ds_read_b128 v[172:175], v245 offset:49152
	ds_read_b128 v[176:179], v246 offset:49152
	ds_read_b128 v[180:183], v245 offset:51200
	ds_read_b128 v[184:187], v246 offset:51200
	s_add_u32 s26, s26, 0x40000
	s_addc_u32 s27, s27, 0
	s_mov_b32 m0, s40
	ds_read_b128 v[188:191], v157 offset:32768
	ds_read_b128 v[192:195], v157 offset:34816
	ds_read_b128 v[196:199], v158 offset:32768
	ds_read_b128 v[200:203], v158 offset:34816
	ds_read_b128 v[204:207], v157 offset:36864
	ds_read_b128 v[208:211], v157 offset:38912
	ds_read_b128 v[212:215], v158 offset:36864
	ds_read_b128 v[216:219], v158 offset:38912
	global_load_lds_dwordx4 v130, s[26:27]
	s_mov_b32 m0, s41
	s_nop 0
	global_load_lds_dwordx4 v134, s[26:27]
	s_waitcnt vmcnt(8)
	s_waitcnt lgkmcnt(0)
	s_barrier
	s_setprio 1
	s_waitcnt lgkmcnt(0)
	v_mfma_f32_16x16x32_bf16 v[126:129], v[150:153], v[188:191], v[126:129]
	v_mfma_f32_16x16x32_bf16 v[118:121], v[164:167], v[188:191], v[118:121]
	v_mfma_f32_16x16x32_bf16 v[110:113], v[150:153], v[192:195], v[110:113]
	v_mfma_f32_16x16x32_bf16 v[102:105], v[164:167], v[192:195], v[102:105]
	v_mfma_f32_16x16x32_bf16 v[94:97], v[150:153], v[204:207], v[94:97]
	v_mfma_f32_16x16x32_bf16 v[86:89], v[164:167], v[204:207], v[86:89]
	v_mfma_f32_16x16x32_bf16 v[78:81], v[150:153], v[208:211], v[78:81]
	v_mfma_f32_16x16x32_bf16 v[70:73], v[164:167], v[208:211], v[70:73]
	v_mfma_f32_16x16x32_bf16 v[126:129], v[160:163], v[196:199], v[126:129]
	v_mfma_f32_16x16x32_bf16 v[118:121], v[168:171], v[196:199], v[118:121]
	v_mfma_f32_16x16x32_bf16 v[110:113], v[160:163], v[200:203], v[110:113]
	v_mfma_f32_16x16x32_bf16 v[102:105], v[168:171], v[200:203], v[102:105]
	v_mfma_f32_16x16x32_bf16 v[94:97], v[160:163], v[212:215], v[94:97]
	v_mfma_f32_16x16x32_bf16 v[86:89], v[168:171], v[212:215], v[86:89]
	v_mfma_f32_16x16x32_bf16 v[78:81], v[160:163], v[216:219], v[78:81]
	v_mfma_f32_16x16x32_bf16 v[70:73], v[168:171], v[216:219], v[70:73]
	s_setprio 0
	s_setprio 1
	v_mfma_f32_16x16x32_bf16 v[122:125], v[172:175], v[188:191], v[122:125]
	v_mfma_f32_16x16x32_bf16 v[114:117], v[180:183], v[188:191], v[114:117]
	v_mfma_f32_16x16x32_bf16 v[106:109], v[172:175], v[192:195], v[106:109]
	v_mfma_f32_16x16x32_bf16 v[98:101], v[180:183], v[192:195], v[98:101]
	v_mfma_f32_16x16x32_bf16 v[90:93], v[172:175], v[204:207], v[90:93]
	v_mfma_f32_16x16x32_bf16 v[82:85], v[180:183], v[204:207], v[82:85]
	v_mfma_f32_16x16x32_bf16 v[74:77], v[172:175], v[208:211], v[74:77]
	v_mfma_f32_16x16x32_bf16 v[66:69], v[180:183], v[208:211], v[66:69]
	v_mfma_f32_16x16x32_bf16 v[122:125], v[176:179], v[196:199], v[122:125]
	v_mfma_f32_16x16x32_bf16 v[114:117], v[184:187], v[196:199], v[114:117]
	v_mfma_f32_16x16x32_bf16 v[106:109], v[176:179], v[200:203], v[106:109]
	v_mfma_f32_16x16x32_bf16 v[98:101], v[184:187], v[200:203], v[98:101]
	v_mfma_f32_16x16x32_bf16 v[90:93], v[176:179], v[212:215], v[90:93]
	v_mfma_f32_16x16x32_bf16 v[82:85], v[184:187], v[212:215], v[82:85]
	v_mfma_f32_16x16x32_bf16 v[74:77], v[176:179], v[216:219], v[74:77]
	v_mfma_f32_16x16x32_bf16 v[66:69], v[184:187], v[216:219], v[66:69]
	s_setprio 0
	s_barrier
	s_add_i32 s26, s64, s21
	s_add_i32 m0, s26, 0xffffff80
	ds_read_b128 v[188:191], v157 offset:49152
	ds_read_b128 v[192:195], v157 offset:51200
	ds_read_b128 v[196:199], v158 offset:49152
	ds_read_b128 v[200:203], v158 offset:51200
	ds_read_b128 v[204:207], v157 offset:53248
	ds_read_b128 v[208:211], v157 offset:55296
	ds_read_b128 v[212:215], v158 offset:53248
	ds_read_b128 v[216:219], v158 offset:55296
	global_load_lds_dwordx4 v132, s[24:25] offset:128
	s_add_i32 m0, s26, 0x1f80
	s_add_i32 s26, s65, s21
	global_load_lds_dwordx4 v136, s[24:25] offset:128
	s_add_u32 s24, s24, 0x40080
	s_addc_u32 s25, s25, 0
	s_mov_b32 m0, s26
	s_nop 0
	global_load_lds_dwordx4 v132, s[24:25]
	s_add_i32 m0, s26, 0x2000
	s_nop 0
	global_load_lds_dwordx4 v136, s[24:25]
	s_add_i32 m0, s44, 0xffffff80
	s_nop 0
	global_load_lds_dwordx4 v130, s[98:99] offset:128
	s_add_i32 m0, s45, 0xffffff80
	s_nop 0
	global_load_lds_dwordx4 v134, s[98:99] offset:128
	s_waitcnt vmcnt(8)
	s_waitcnt lgkmcnt(0)
	s_barrier
	s_setprio 1
	s_waitcnt lgkmcnt(0)
	v_mfma_f32_16x16x32_bf16 v[62:65], v[150:153], v[188:191], v[62:65]
	v_mfma_f32_16x16x32_bf16 v[54:57], v[164:167], v[188:191], v[54:57]
	v_mfma_f32_16x16x32_bf16 v[46:49], v[150:153], v[192:195], v[46:49]
	v_mfma_f32_16x16x32_bf16 v[38:41], v[164:167], v[192:195], v[38:41]
	v_mfma_f32_16x16x32_bf16 v[30:33], v[150:153], v[204:207], v[30:33]
	v_mfma_f32_16x16x32_bf16 v[22:25], v[164:167], v[204:207], v[22:25]
	v_mfma_f32_16x16x32_bf16 v[14:17], v[150:153], v[208:211], v[14:17]
	v_mfma_f32_16x16x32_bf16 v[6:9], v[164:167], v[208:211], v[6:9]
	v_mfma_f32_16x16x32_bf16 v[62:65], v[160:163], v[196:199], v[62:65]
	v_mfma_f32_16x16x32_bf16 v[54:57], v[168:171], v[196:199], v[54:57]
	v_mfma_f32_16x16x32_bf16 v[46:49], v[160:163], v[200:203], v[46:49]
	v_mfma_f32_16x16x32_bf16 v[38:41], v[168:171], v[200:203], v[38:41]
	v_mfma_f32_16x16x32_bf16 v[30:33], v[160:163], v[212:215], v[30:33]
	v_mfma_f32_16x16x32_bf16 v[22:25], v[168:171], v[212:215], v[22:25]
	v_mfma_f32_16x16x32_bf16 v[14:17], v[160:163], v[216:219], v[14:17]
	v_mfma_f32_16x16x32_bf16 v[6:9], v[168:171], v[216:219], v[6:9]
	s_setprio 0
	s_setprio 1
	v_mfma_f32_16x16x32_bf16 v[58:61], v[172:175], v[188:191], v[58:61]
	v_mfma_f32_16x16x32_bf16 v[50:53], v[180:183], v[188:191], v[50:53]
	v_mfma_f32_16x16x32_bf16 v[42:45], v[172:175], v[192:195], v[42:45]
	v_mfma_f32_16x16x32_bf16 v[34:37], v[180:183], v[192:195], v[34:37]
	v_mfma_f32_16x16x32_bf16 v[26:29], v[172:175], v[204:207], v[26:29]
	v_mfma_f32_16x16x32_bf16 v[18:21], v[180:183], v[204:207], v[18:21]
	v_mfma_f32_16x16x32_bf16 v[10:13], v[172:175], v[208:211], v[10:13]
	v_mfma_f32_16x16x32_bf16 v[2:5], v[180:183], v[208:211], v[2:5]
	v_mfma_f32_16x16x32_bf16 v[58:61], v[176:179], v[196:199], v[58:61]
	v_mfma_f32_16x16x32_bf16 v[50:53], v[184:187], v[196:199], v[50:53]
	v_mfma_f32_16x16x32_bf16 v[42:45], v[176:179], v[200:203], v[42:45]
	v_mfma_f32_16x16x32_bf16 v[34:37], v[184:187], v[200:203], v[34:37]
	v_mfma_f32_16x16x32_bf16 v[26:29], v[176:179], v[212:215], v[26:29]
	v_mfma_f32_16x16x32_bf16 v[18:21], v[184:187], v[212:215], v[18:21]
	v_mfma_f32_16x16x32_bf16 v[10:13], v[176:179], v[216:219], v[10:13]
	v_mfma_f32_16x16x32_bf16 v[2:5], v[184:187], v[216:219], v[2:5]
	s_setprio 0
	s_barrier
	s_add_i32 s63, s63, 2
	s_add_u32 s22, s22, 0x100
	s_addc_u32 s23, s23, 0
	s_add_u32 s61, s61, 0x100
	s_addc_u32 s62, s62, 0
	s_cmp_gt_u32 s63, 13
	s_cbranch_scc1 .LBB0_1725

.Lpeel_5:
	s_mov_b32 s100, 0
	ds_read_b128 v[150:153], v245
	ds_read_b128 v[160:163], v246
	ds_read_b128 v[164:167], v245 offset:2048
	ds_read_b128 v[168:171], v246 offset:2048
	ds_read_b128 v[172:175], v245 offset:16384
	ds_read_b128 v[176:179], v246 offset:16384
	ds_read_b128 v[180:183], v245 offset:18432
	ds_read_b128 v[184:187], v246 offset:18432
	s_add_u32 s26, s22, 0xfffc0080
	s_addc_u32 s27, s23, -1
	s_and_b64 s[24:25], s[24:25], exec
	s_cselect_b32 s27, s13, s27
	s_cselect_b32 s26, s58, s26
	s_cselect_b32 s25, s5, s62
	s_cselect_b32 s24, s59, s61
	s_add_i32 m0, s38, 0xc000
	ds_read_b128 v[188:191], v157
	s_waitcnt lgkmcnt(0)
	ds_read_b128 v[192:195], v157 offset:2048
	ds_read_b128 v[196:199], v158
	ds_read_b128 v[200:203], v158 offset:2048
	ds_read_b128 v[204:207], v157 offset:4096
	ds_read_b128 v[208:211], v157 offset:6144
	ds_read_b128 v[212:215], v158 offset:4096
	ds_read_b128 v[216:219], v158 offset:6144
	global_load_lds_dwordx4 v140, s[22:23]
	s_add_i32 m0, s38, 0xe000
	s_nop 0
	global_load_lds_dwordx4 v142, s[22:23]
	s_waitcnt vmcnt(8)
	s_waitcnt lgkmcnt(0)
	s_barrier
	s_setprio 1
	v_mfma_f32_16x16x32_bf16 v[126:129], v[150:153], v[188:191], 0
	v_mfma_f32_16x16x32_bf16 v[118:121], v[164:167], v[188:191], 0
	s_waitcnt lgkmcnt(0)
	v_mfma_f32_16x16x32_bf16 v[110:113], v[150:153], v[192:195], 0
	v_mfma_f32_16x16x32_bf16 v[102:105], v[164:167], v[192:195], 0
	v_mfma_f32_16x16x32_bf16 v[94:97], v[150:153], v[204:207], 0
	v_mfma_f32_16x16x32_bf16 v[86:89], v[164:167], v[204:207], 0
	v_mfma_f32_16x16x32_bf16 v[78:81], v[150:153], v[208:211], 0
	v_mfma_f32_16x16x32_bf16 v[70:73], v[164:167], v[208:211], 0
	v_mfma_f32_16x16x32_bf16 v[126:129], v[160:163], v[196:199], v[126:129]
	v_mfma_f32_16x16x32_bf16 v[118:121], v[168:171], v[196:199], v[118:121]
	v_mfma_f32_16x16x32_bf16 v[110:113], v[160:163], v[200:203], v[110:113]
	v_mfma_f32_16x16x32_bf16 v[102:105], v[168:171], v[200:203], v[102:105]
	v_mfma_f32_16x16x32_bf16 v[94:97], v[160:163], v[212:215], v[94:97]
	v_mfma_f32_16x16x32_bf16 v[86:89], v[168:171], v[212:215], v[86:89]
	v_mfma_f32_16x16x32_bf16 v[78:81], v[160:163], v[216:219], v[78:81]
	v_mfma_f32_16x16x32_bf16 v[70:73], v[168:171], v[216:219], v[70:73]
	s_setprio 0
	s_setprio 1
	v_mfma_f32_16x16x32_bf16 v[122:125], v[172:175], v[188:191], 0
	v_mfma_f32_16x16x32_bf16 v[114:117], v[180:183], v[188:191], 0
	v_mfma_f32_16x16x32_bf16 v[106:109], v[172:175], v[192:195], 0
	v_mfma_f32_16x16x32_bf16 v[98:101], v[180:183], v[192:195], 0
	v_mfma_f32_16x16x32_bf16 v[90:93], v[172:175], v[204:207], 0
	v_mfma_f32_16x16x32_bf16 v[82:85], v[180:183], v[204:207], 0
	v_mfma_f32_16x16x32_bf16 v[74:77], v[172:175], v[208:211], 0
	v_mfma_f32_16x16x32_bf16 v[66:69], v[180:183], v[208:211], 0
	v_mfma_f32_16x16x32_bf16 v[122:125], v[176:179], v[196:199], v[122:125]
	v_mfma_f32_16x16x32_bf16 v[114:117], v[184:187], v[196:199], v[114:117]
	v_mfma_f32_16x16x32_bf16 v[106:109], v[176:179], v[200:203], v[106:109]
	v_mfma_f32_16x16x32_bf16 v[98:101], v[184:187], v[200:203], v[98:101]
	v_mfma_f32_16x16x32_bf16 v[90:93], v[176:179], v[212:215], v[90:93]
	v_mfma_f32_16x16x32_bf16 v[82:85], v[184:187], v[212:215], v[82:85]
	v_mfma_f32_16x16x32_bf16 v[74:77], v[176:179], v[216:219], v[74:77]
	v_mfma_f32_16x16x32_bf16 v[66:69], v[184:187], v[216:219], v[66:69]
	s_setprio 0
	s_barrier
	s_add_i32 s64, s49, s21
	s_mov_b32 m0, s64
	ds_read_b128 v[188:191], v157 offset:16384
	ds_read_b128 v[192:195], v157 offset:18432
	ds_read_b128 v[196:199], v158 offset:16384
	ds_read_b128 v[200:203], v158 offset:18432
	ds_read_b128 v[204:207], v157 offset:20480
	ds_read_b128 v[208:211], v157 offset:22528
	ds_read_b128 v[212:215], v158 offset:20480
	ds_read_b128 v[216:219], v158 offset:22528
	global_load_lds_dwordx4 v132, s[24:25]
	s_add_i32 m0, s64, 0x2000
	s_add_u32 s64, s24, 0x40000
	s_addc_u32 s65, s25, 0
	s_add_i32 s66, s51, s21
	global_load_lds_dwordx4 v136, s[24:25]
	s_mov_b32 m0, s66
	s_mov_b64 s[98:99], s[26:27]
	global_load_lds_dwordx4 v132, s[64:65]
	s_add_i32 m0, s66, 0x2000
	s_nop 0
	global_load_lds_dwordx4 v136, s[64:65]
	s_mov_b32 m0, s38
	s_nop 0
	global_load_lds_dwordx4 v130, s[26:27]
	s_mov_b32 m0, s39
	s_nop 0
	global_load_lds_dwordx4 v134, s[26:27]
	s_waitcnt vmcnt(8)
	s_waitcnt lgkmcnt(0)
	s_barrier
	s_setprio 1
	s_waitcnt lgkmcnt(0)
	v_mfma_f32_16x16x32_bf16 v[62:65], v[150:153], v[188:191], 0
	v_mfma_f32_16x16x32_bf16 v[54:57], v[164:167], v[188:191], 0
	v_mfma_f32_16x16x32_bf16 v[46:49], v[150:153], v[192:195], 0
	v_mfma_f32_16x16x32_bf16 v[38:41], v[164:167], v[192:195], 0
	v_mfma_f32_16x16x32_bf16 v[30:33], v[150:153], v[204:207], 0
	v_mfma_f32_16x16x32_bf16 v[22:25], v[164:167], v[204:207], 0
	v_mfma_f32_16x16x32_bf16 v[14:17], v[150:153], v[208:211], 0
	v_mfma_f32_16x16x32_bf16 v[6:9], v[164:167], v[208:211], 0
	v_mfma_f32_16x16x32_bf16 v[62:65], v[160:163], v[196:199], v[62:65]
	v_mfma_f32_16x16x32_bf16 v[54:57], v[168:171], v[196:199], v[54:57]
	v_mfma_f32_16x16x32_bf16 v[46:49], v[160:163], v[200:203], v[46:49]
	v_mfma_f32_16x16x32_bf16 v[38:41], v[168:171], v[200:203], v[38:41]
	v_mfma_f32_16x16x32_bf16 v[30:33], v[160:163], v[212:215], v[30:33]
	v_mfma_f32_16x16x32_bf16 v[22:25], v[168:171], v[212:215], v[22:25]
	v_mfma_f32_16x16x32_bf16 v[14:17], v[160:163], v[216:219], v[14:17]
	v_mfma_f32_16x16x32_bf16 v[6:9], v[168:171], v[216:219], v[6:9]
	s_setprio 0
	s_setprio 1
	v_mfma_f32_16x16x32_bf16 v[58:61], v[172:175], v[188:191], 0
	v_mfma_f32_16x16x32_bf16 v[50:53], v[180:183], v[188:191], 0
	v_mfma_f32_16x16x32_bf16 v[42:45], v[172:175], v[192:195], 0
	v_mfma_f32_16x16x32_bf16 v[34:37], v[180:183], v[192:195], 0
	v_mfma_f32_16x16x32_bf16 v[26:29], v[172:175], v[204:207], 0
	v_mfma_f32_16x16x32_bf16 v[18:21], v[180:183], v[204:207], 0
	v_mfma_f32_16x16x32_bf16 v[10:13], v[172:175], v[208:211], 0
	v_mfma_f32_16x16x32_bf16 v[2:5], v[180:183], v[208:211], 0
	v_mfma_f32_16x16x32_bf16 v[58:61], v[176:179], v[196:199], v[58:61]
	v_mfma_f32_16x16x32_bf16 v[50:53], v[184:187], v[196:199], v[50:53]
	v_mfma_f32_16x16x32_bf16 v[42:45], v[176:179], v[200:203], v[42:45]
	v_mfma_f32_16x16x32_bf16 v[34:37], v[184:187], v[200:203], v[34:37]
	v_mfma_f32_16x16x32_bf16 v[26:29], v[176:179], v[212:215], v[26:29]
	v_mfma_f32_16x16x32_bf16 v[18:21], v[184:187], v[212:215], v[18:21]
	v_mfma_f32_16x16x32_bf16 v[10:13], v[176:179], v[216:219], v[10:13]
	v_mfma_f32_16x16x32_bf16 v[2:5], v[184:187], v[216:219], v[2:5]
	s_setprio 0
	s_barrier
	s_add_i32 s64, 0, 0x18000
	s_add_i32 s65, 0, 0x1c000
	ds_read_b128 v[150:153], v245 offset:32768
	ds_read_b128 v[160:163], v246 offset:32768
	ds_read_b128 v[164:167], v245 offset:34816
	ds_read_b128 v[168:171], v246 offset:34816
	ds_read_b128 v[172:175], v245 offset:49152
	ds_read_b128 v[176:179], v246 offset:49152
	ds_read_b128 v[180:183], v245 offset:51200
	ds_read_b128 v[184:187], v246 offset:51200
	s_add_u32 s26, s26, 0x40000
	s_addc_u32 s27, s27, 0
	s_mov_b32 m0, s40
	ds_read_b128 v[188:191], v157 offset:32768
	ds_read_b128 v[192:195], v157 offset:34816
	ds_read_b128 v[196:199], v158 offset:32768
	ds_read_b128 v[200:203], v158 offset:34816
	ds_read_b128 v[204:207], v157 offset:36864
	ds_read_b128 v[208:211], v157 offset:38912
	ds_read_b128 v[212:215], v158 offset:36864
	ds_read_b128 v[216:219], v158 offset:38912
	global_load_lds_dwordx4 v130, s[26:27]
	s_mov_b32 m0, s41
	s_nop 0
	global_load_lds_dwordx4 v134, s[26:27]
	s_waitcnt vmcnt(8)
	s_waitcnt lgkmcnt(0)
	s_barrier
	s_setprio 1
	s_waitcnt lgkmcnt(0)
	v_mfma_f32_16x16x32_bf16 v[126:129], v[150:153], v[188:191], v[126:129]
	v_mfma_f32_16x16x32_bf16 v[118:121], v[164:167], v[188:191], v[118:121]
	v_mfma_f32_16x16x32_bf16 v[110:113], v[150:153], v[192:195], v[110:113]
	v_mfma_f32_16x16x32_bf16 v[102:105], v[164:167], v[192:195], v[102:105]
	v_mfma_f32_16x16x32_bf16 v[94:97], v[150:153], v[204:207], v[94:97]
	v_mfma_f32_16x16x32_bf16 v[86:89], v[164:167], v[204:207], v[86:89]
	v_mfma_f32_16x16x32_bf16 v[78:81], v[150:153], v[208:211], v[78:81]
	v_mfma_f32_16x16x32_bf16 v[70:73], v[164:167], v[208:211], v[70:73]
	v_mfma_f32_16x16x32_bf16 v[126:129], v[160:163], v[196:199], v[126:129]
	v_mfma_f32_16x16x32_bf16 v[118:121], v[168:171], v[196:199], v[118:121]
	v_mfma_f32_16x16x32_bf16 v[110:113], v[160:163], v[200:203], v[110:113]
	v_mfma_f32_16x16x32_bf16 v[102:105], v[168:171], v[200:203], v[102:105]
	v_mfma_f32_16x16x32_bf16 v[94:97], v[160:163], v[212:215], v[94:97]
	v_mfma_f32_16x16x32_bf16 v[86:89], v[168:171], v[212:215], v[86:89]
	v_mfma_f32_16x16x32_bf16 v[78:81], v[160:163], v[216:219], v[78:81]
	v_mfma_f32_16x16x32_bf16 v[70:73], v[168:171], v[216:219], v[70:73]
	s_setprio 0
	s_setprio 1
	v_mfma_f32_16x16x32_bf16 v[122:125], v[172:175], v[188:191], v[122:125]
	v_mfma_f32_16x16x32_bf16 v[114:117], v[180:183], v[188:191], v[114:117]
	v_mfma_f32_16x16x32_bf16 v[106:109], v[172:175], v[192:195], v[106:109]
	v_mfma_f32_16x16x32_bf16 v[98:101], v[180:183], v[192:195], v[98:101]
	v_mfma_f32_16x16x32_bf16 v[90:93], v[172:175], v[204:207], v[90:93]
	v_mfma_f32_16x16x32_bf16 v[82:85], v[180:183], v[204:207], v[82:85]
	v_mfma_f32_16x16x32_bf16 v[74:77], v[172:175], v[208:211], v[74:77]
	v_mfma_f32_16x16x32_bf16 v[66:69], v[180:183], v[208:211], v[66:69]
	v_mfma_f32_16x16x32_bf16 v[122:125], v[176:179], v[196:199], v[122:125]
	v_mfma_f32_16x16x32_bf16 v[114:117], v[184:187], v[196:199], v[114:117]
	v_mfma_f32_16x16x32_bf16 v[106:109], v[176:179], v[200:203], v[106:109]
	v_mfma_f32_16x16x32_bf16 v[98:101], v[184:187], v[200:203], v[98:101]
	v_mfma_f32_16x16x32_bf16 v[90:93], v[176:179], v[212:215], v[90:93]
	v_mfma_f32_16x16x32_bf16 v[82:85], v[184:187], v[212:215], v[82:85]
	v_mfma_f32_16x16x32_bf16 v[74:77], v[176:179], v[216:219], v[74:77]
	v_mfma_f32_16x16x32_bf16 v[66:69], v[184:187], v[216:219], v[66:69]
	s_setprio 0
	s_barrier
	s_add_i32 s26, s64, s21
	s_add_i32 m0, s26, 0xffffff80
	ds_read_b128 v[188:191], v157 offset:49152
	ds_read_b128 v[192:195], v157 offset:51200
	ds_read_b128 v[196:199], v158 offset:49152
	ds_read_b128 v[200:203], v158 offset:51200
	ds_read_b128 v[204:207], v157 offset:53248
	ds_read_b128 v[208:211], v157 offset:55296
	ds_read_b128 v[212:215], v158 offset:53248
	ds_read_b128 v[216:219], v158 offset:55296
	global_load_lds_dwordx4 v132, s[24:25] offset:128
	s_add_i32 m0, s26, 0x1f80
	s_add_i32 s26, s65, s21
	global_load_lds_dwordx4 v136, s[24:25] offset:128
	s_add_u32 s24, s24, 0x40080
	s_addc_u32 s25, s25, 0
	s_mov_b32 m0, s26
	s_nop 0
	global_load_lds_dwordx4 v132, s[24:25]
	s_add_i32 m0, s26, 0x2000
	s_nop 0
	global_load_lds_dwordx4 v136, s[24:25]
	s_add_i32 m0, s44, 0xffffff80
	s_nop 0
	global_load_lds_dwordx4 v130, s[98:99] offset:128
	s_add_i32 m0, s45, 0xffffff80
	s_nop 0
	global_load_lds_dwordx4 v134, s[98:99] offset:128
	s_waitcnt vmcnt(8)
	s_waitcnt lgkmcnt(0)
	s_barrier
	s_setprio 1
	s_waitcnt lgkmcnt(0)
	v_mfma_f32_16x16x32_bf16 v[62:65], v[150:153], v[188:191], v[62:65]
	v_mfma_f32_16x16x32_bf16 v[54:57], v[164:167], v[188:191], v[54:57]
	v_mfma_f32_16x16x32_bf16 v[46:49], v[150:153], v[192:195], v[46:49]
	v_mfma_f32_16x16x32_bf16 v[38:41], v[164:167], v[192:195], v[38:41]
	v_mfma_f32_16x16x32_bf16 v[30:33], v[150:153], v[204:207], v[30:33]
	v_mfma_f32_16x16x32_bf16 v[22:25], v[164:167], v[204:207], v[22:25]
	v_mfma_f32_16x16x32_bf16 v[14:17], v[150:153], v[208:211], v[14:17]
	v_mfma_f32_16x16x32_bf16 v[6:9], v[164:167], v[208:211], v[6:9]
	v_mfma_f32_16x16x32_bf16 v[62:65], v[160:163], v[196:199], v[62:65]
	v_mfma_f32_16x16x32_bf16 v[54:57], v[168:171], v[196:199], v[54:57]
	v_mfma_f32_16x16x32_bf16 v[46:49], v[160:163], v[200:203], v[46:49]
	v_mfma_f32_16x16x32_bf16 v[38:41], v[168:171], v[200:203], v[38:41]
	v_mfma_f32_16x16x32_bf16 v[30:33], v[160:163], v[212:215], v[30:33]
	v_mfma_f32_16x16x32_bf16 v[22:25], v[168:171], v[212:215], v[22:25]
	v_mfma_f32_16x16x32_bf16 v[14:17], v[160:163], v[216:219], v[14:17]
	v_mfma_f32_16x16x32_bf16 v[6:9], v[168:171], v[216:219], v[6:9]
	s_setprio 0
	s_setprio 1
	v_mfma_f32_16x16x32_bf16 v[58:61], v[172:175], v[188:191], v[58:61]
	v_mfma_f32_16x16x32_bf16 v[50:53], v[180:183], v[188:191], v[50:53]
	v_mfma_f32_16x16x32_bf16 v[42:45], v[172:175], v[192:195], v[42:45]
	v_mfma_f32_16x16x32_bf16 v[34:37], v[180:183], v[192:195], v[34:37]
	v_mfma_f32_16x16x32_bf16 v[26:29], v[172:175], v[204:207], v[26:29]
	v_mfma_f32_16x16x32_bf16 v[18:21], v[180:183], v[204:207], v[18:21]
	v_mfma_f32_16x16x32_bf16 v[10:13], v[172:175], v[208:211], v[10:13]
	v_mfma_f32_16x16x32_bf16 v[2:5], v[180:183], v[208:211], v[2:5]
	v_mfma_f32_16x16x32_bf16 v[58:61], v[176:179], v[196:199], v[58:61]
	v_mfma_f32_16x16x32_bf16 v[50:53], v[184:187], v[196:199], v[50:53]
	v_mfma_f32_16x16x32_bf16 v[42:45], v[176:179], v[200:203], v[42:45]
	v_mfma_f32_16x16x32_bf16 v[34:37], v[184:187], v[200:203], v[34:37]
	v_mfma_f32_16x16x32_bf16 v[26:29], v[176:179], v[212:215], v[26:29]
	v_mfma_f32_16x16x32_bf16 v[18:21], v[184:187], v[212:215], v[18:21]
	v_mfma_f32_16x16x32_bf16 v[10:13], v[176:179], v[216:219], v[10:13]
	v_mfma_f32_16x16x32_bf16 v[2:5], v[184:187], v[216:219], v[2:5]
	s_setprio 0
	s_barrier
	s_add_i32 s63, s63, 2
	s_add_u32 s22, s22, 0x100
	s_addc_u32 s23, s23, 0
	s_add_u32 s61, s61, 0x100
	s_addc_u32 s62, s62, 0
	s_cmp_gt_u32 s63, 13
	s_cbranch_scc1 .LBB0_1725
	s_branch .LBB0_1722

.LBB0_1827:
	s_cmp_lg_u32 s100, 0
	s_cbranch_scc1 .Lpeel_6
	ds_read_b128 v[120:123], v220
	ds_read_b128 v[128:131], v221
	ds_read_b128 v[136:139], v222
	ds_read_b128 v[140:143], v223
	ds_read_b128 v[144:147], v224
	ds_read_b128 v[148:151], v225
	ds_read_b128 v[152:155], v226
	ds_read_b128 v[156:159], v227
	s_add_u32 s40, s4, 0xfff50080
	s_addc_u32 s41, s5, -1
	s_cmp_eq_u32 s66, 40
	s_cselect_b32 s43, s29, s41
	s_cselect_b32 s42, s28, s40
	s_cselect_b32 s41, s35, s65
	s_cselect_b32 s40, s34, s64
	s_add_i32 m0, s44, 0xc000
	ds_read_b128 v[160:163], v228
	ds_read_b128 v[164:167], v228 offset:2048
	ds_read_b128 v[168:171], v229
	ds_read_b128 v[172:175], v229 offset:2048
	ds_read_b128 v[176:179], v228 offset:4096
	ds_read_b128 v[180:183], v228 offset:6144
	ds_read_b128 v[184:187], v229 offset:4096
	ds_read_b128 v[188:191], v229 offset:6144
	global_load_lds_dwordx4 v202, s[4:5]
	s_add_i32 m0, s44, 0xe000
	s_nop 0
	global_load_lds_dwordx4 v204, s[4:5]
	s_waitcnt vmcnt(8)
	s_waitcnt lgkmcnt(0)
	s_barrier
	s_setprio 1
	s_waitcnt lgkmcnt(0)
	v_mfma_f32_16x16x32_bf16 v[132:135], v[120:123], v[160:163], v[132:135]
	v_mfma_f32_16x16x32_bf16 v[124:127], v[136:139], v[160:163], v[124:127]
	v_mfma_f32_16x16x32_bf16 v[108:111], v[120:123], v[164:167], v[108:111]
	v_mfma_f32_16x16x32_bf16 v[104:107], v[136:139], v[164:167], v[104:107]
	v_mfma_f32_16x16x32_bf16 v[92:95], v[120:123], v[176:179], v[92:95]
	v_mfma_f32_16x16x32_bf16 v[88:91], v[136:139], v[176:179], v[88:91]
	v_mfma_f32_16x16x32_bf16 v[76:79], v[120:123], v[180:183], v[76:79]
	v_mfma_f32_16x16x32_bf16 v[72:75], v[136:139], v[180:183], v[72:75]
	v_mfma_f32_16x16x32_bf16 v[132:135], v[128:131], v[168:171], v[132:135]
	v_mfma_f32_16x16x32_bf16 v[124:127], v[140:143], v[168:171], v[124:127]
	v_mfma_f32_16x16x32_bf16 v[108:111], v[128:131], v[172:175], v[108:111]
	v_mfma_f32_16x16x32_bf16 v[104:107], v[140:143], v[172:175], v[104:107]
	v_mfma_f32_16x16x32_bf16 v[92:95], v[128:131], v[184:187], v[92:95]
	v_mfma_f32_16x16x32_bf16 v[88:91], v[140:143], v[184:187], v[88:91]
	v_mfma_f32_16x16x32_bf16 v[76:79], v[128:131], v[188:191], v[76:79]
	v_mfma_f32_16x16x32_bf16 v[72:75], v[140:143], v[188:191], v[72:75]
	s_setprio 0
	s_setprio 1
	v_mfma_f32_16x16x32_bf16 v[116:119], v[144:147], v[160:163], v[116:119]
	v_mfma_f32_16x16x32_bf16 v[112:115], v[152:155], v[160:163], v[112:115]
	v_mfma_f32_16x16x32_bf16 v[100:103], v[144:147], v[164:167], v[100:103]
	v_mfma_f32_16x16x32_bf16 v[96:99], v[152:155], v[164:167], v[96:99]
	v_mfma_f32_16x16x32_bf16 v[84:87], v[144:147], v[176:179], v[84:87]
	v_mfma_f32_16x16x32_bf16 v[80:83], v[152:155], v[176:179], v[80:83]
	v_mfma_f32_16x16x32_bf16 v[68:71], v[144:147], v[180:183], v[68:71]
	v_mfma_f32_16x16x32_bf16 v[64:67], v[152:155], v[180:183], v[64:67]
	v_mfma_f32_16x16x32_bf16 v[116:119], v[148:151], v[168:171], v[116:119]
	v_mfma_f32_16x16x32_bf16 v[112:115], v[156:159], v[168:171], v[112:115]
	v_mfma_f32_16x16x32_bf16 v[100:103], v[148:151], v[172:175], v[100:103]
	v_mfma_f32_16x16x32_bf16 v[96:99], v[156:159], v[172:175], v[96:99]
	v_mfma_f32_16x16x32_bf16 v[84:87], v[148:151], v[184:187], v[84:87]
	v_mfma_f32_16x16x32_bf16 v[80:83], v[156:159], v[184:187], v[80:83]
	v_mfma_f32_16x16x32_bf16 v[68:71], v[148:151], v[188:191], v[68:71]
	v_mfma_f32_16x16x32_bf16 v[64:67], v[156:159], v[188:191], v[64:67]
	s_setprio 0
	s_barrier
	s_add_i32 s67, s58, s39
	s_mov_b32 m0, s67
	ds_read_b128 v[160:163], v228 offset:16384
	ds_read_b128 v[164:167], v228 offset:18432
	ds_read_b128 v[168:171], v229 offset:16384
	ds_read_b128 v[172:175], v229 offset:18432
	ds_read_b128 v[176:179], v228 offset:20480
	ds_read_b128 v[180:183], v228 offset:22528
	ds_read_b128 v[184:187], v229 offset:20480
	ds_read_b128 v[188:191], v229 offset:22528
	global_load_lds_dwordx4 v194, s[40:41]
	s_add_i32 m0, s67, 0x2000
	s_add_u32 s68, s40, 0xb0000
	s_addc_u32 s69, s41, 0
	s_add_i32 s67, s59, s39
	global_load_lds_dwordx4 v198, s[40:41]
	s_mov_b32 m0, s67
	s_mov_b64 s[98:99], s[42:43]
	global_load_lds_dwordx4 v194, s[68:69]
	s_add_i32 m0, s67, 0x2000
	s_nop 0
	global_load_lds_dwordx4 v198, s[68:69]
	s_mov_b32 m0, s44
	s_nop 0
	global_load_lds_dwordx4 v192, s[42:43]
	s_mov_b32 m0, s45
	s_nop 0
	global_load_lds_dwordx4 v196, s[42:43]
	s_waitcnt vmcnt(8)
	s_waitcnt lgkmcnt(0)
	s_barrier
	s_setprio 1
	s_waitcnt lgkmcnt(0)
	v_mfma_f32_16x16x32_bf16 v[60:63], v[120:123], v[160:163], v[60:63]
	v_mfma_f32_16x16x32_bf16 v[56:59], v[136:139], v[160:163], v[56:59]
	v_mfma_f32_16x16x32_bf16 v[44:47], v[120:123], v[164:167], v[44:47]
	v_mfma_f32_16x16x32_bf16 v[40:43], v[136:139], v[164:167], v[40:43]
	v_mfma_f32_16x16x32_bf16 v[28:31], v[120:123], v[176:179], v[28:31]
	v_mfma_f32_16x16x32_bf16 v[24:27], v[136:139], v[176:179], v[24:27]
	v_mfma_f32_16x16x32_bf16 v[12:15], v[120:123], v[180:183], v[12:15]
	v_mfma_f32_16x16x32_bf16 v[8:11], v[136:139], v[180:183], v[8:11]
	v_mfma_f32_16x16x32_bf16 v[60:63], v[128:131], v[168:171], v[60:63]
	v_mfma_f32_16x16x32_bf16 v[56:59], v[140:143], v[168:171], v[56:59]
	v_mfma_f32_16x16x32_bf16 v[44:47], v[128:131], v[172:175], v[44:47]
	v_mfma_f32_16x16x32_bf16 v[40:43], v[140:143], v[172:175], v[40:43]
	v_mfma_f32_16x16x32_bf16 v[28:31], v[128:131], v[184:187], v[28:31]
	v_mfma_f32_16x16x32_bf16 v[24:27], v[140:143], v[184:187], v[24:27]
	v_mfma_f32_16x16x32_bf16 v[12:15], v[128:131], v[188:191], v[12:15]
	v_mfma_f32_16x16x32_bf16 v[8:11], v[140:143], v[188:191], v[8:11]
	s_setprio 0
	s_setprio 1
	v_mfma_f32_16x16x32_bf16 v[52:55], v[144:147], v[160:163], v[52:55]
	v_mfma_f32_16x16x32_bf16 v[48:51], v[152:155], v[160:163], v[48:51]
	v_mfma_f32_16x16x32_bf16 v[36:39], v[144:147], v[164:167], v[36:39]
	v_mfma_f32_16x16x32_bf16 v[32:35], v[152:155], v[164:167], v[32:35]
	v_mfma_f32_16x16x32_bf16 v[20:23], v[144:147], v[176:179], v[20:23]
	v_mfma_f32_16x16x32_bf16 v[16:19], v[152:155], v[176:179], v[16:19]
	v_mfma_f32_16x16x32_bf16 v[4:7], v[144:147], v[180:183], v[4:7]
	v_mfma_f32_16x16x32_bf16 v[0:3], v[152:155], v[180:183], v[0:3]
	v_mfma_f32_16x16x32_bf16 v[52:55], v[148:151], v[168:171], v[52:55]
	v_mfma_f32_16x16x32_bf16 v[48:51], v[156:159], v[168:171], v[48:51]
	v_mfma_f32_16x16x32_bf16 v[36:39], v[148:151], v[172:175], v[36:39]
	v_mfma_f32_16x16x32_bf16 v[32:35], v[156:159], v[172:175], v[32:35]
	v_mfma_f32_16x16x32_bf16 v[20:23], v[148:151], v[184:187], v[20:23]
	v_mfma_f32_16x16x32_bf16 v[16:19], v[156:159], v[184:187], v[16:19]
	v_mfma_f32_16x16x32_bf16 v[4:7], v[148:151], v[188:191], v[4:7]
	v_mfma_f32_16x16x32_bf16 v[0:3], v[156:159], v[188:191], v[0:3]
	s_setprio 0
	s_barrier
	s_add_i32 s67, 0, 0x18000
	s_add_i32 s68, 0, 0x1c000
	ds_read_b128 v[120:123], v245 offset:32768
	ds_read_b128 v[128:131], v246 offset:32768
	ds_read_b128 v[136:139], v230
	ds_read_b128 v[140:143], v231
	ds_read_b128 v[144:147], v245 offset:49152
	ds_read_b128 v[148:151], v246 offset:49152
	ds_read_b128 v[152:155], v232
	ds_read_b128 v[156:159], v233
	s_add_u32 s42, s42, 0xb0000
	s_addc_u32 s43, s43, 0
	s_mov_b32 m0, s46
	ds_read_b128 v[160:163], v228 offset:32768
	ds_read_b128 v[164:167], v228 offset:34816
	ds_read_b128 v[168:171], v229 offset:32768
	ds_read_b128 v[172:175], v229 offset:34816
	ds_read_b128 v[176:179], v228 offset:36864
	ds_read_b128 v[180:183], v228 offset:38912
	ds_read_b128 v[184:187], v229 offset:36864
	ds_read_b128 v[188:191], v229 offset:38912
	global_load_lds_dwordx4 v192, s[42:43]
	s_mov_b32 m0, s47
	s_nop 0
	global_load_lds_dwordx4 v196, s[42:43]
	s_waitcnt vmcnt(8)
	s_waitcnt lgkmcnt(0)
	s_barrier
	s_setprio 1
	s_waitcnt lgkmcnt(0)
	v_mfma_f32_16x16x32_bf16 v[132:135], v[120:123], v[160:163], v[132:135]
	v_mfma_f32_16x16x32_bf16 v[124:127], v[136:139], v[160:163], v[124:127]
	v_mfma_f32_16x16x32_bf16 v[108:111], v[120:123], v[164:167], v[108:111]
	v_mfma_f32_16x16x32_bf16 v[104:107], v[136:139], v[164:167], v[104:107]
	v_mfma_f32_16x16x32_bf16 v[92:95], v[120:123], v[176:179], v[92:95]
	v_mfma_f32_16x16x32_bf16 v[88:91], v[136:139], v[176:179], v[88:91]
	v_mfma_f32_16x16x32_bf16 v[76:79], v[120:123], v[180:183], v[76:79]
	v_mfma_f32_16x16x32_bf16 v[72:75], v[136:139], v[180:183], v[72:75]
	v_mfma_f32_16x16x32_bf16 v[132:135], v[128:131], v[168:171], v[132:135]
	v_mfma_f32_16x16x32_bf16 v[124:127], v[140:143], v[168:171], v[124:127]
	v_mfma_f32_16x16x32_bf16 v[108:111], v[128:131], v[172:175], v[108:111]
	v_mfma_f32_16x16x32_bf16 v[104:107], v[140:143], v[172:175], v[104:107]
	v_mfma_f32_16x16x32_bf16 v[92:95], v[128:131], v[184:187], v[92:95]
	v_mfma_f32_16x16x32_bf16 v[88:91], v[140:143], v[184:187], v[88:91]
	v_mfma_f32_16x16x32_bf16 v[76:79], v[128:131], v[188:191], v[76:79]
	v_mfma_f32_16x16x32_bf16 v[72:75], v[140:143], v[188:191], v[72:75]
	s_setprio 0
	s_setprio 1
	v_mfma_f32_16x16x32_bf16 v[116:119], v[144:147], v[160:163], v[116:119]
	v_mfma_f32_16x16x32_bf16 v[112:115], v[152:155], v[160:163], v[112:115]
	v_mfma_f32_16x16x32_bf16 v[100:103], v[144:147], v[164:167], v[100:103]
	v_mfma_f32_16x16x32_bf16 v[96:99], v[152:155], v[164:167], v[96:99]
	v_mfma_f32_16x16x32_bf16 v[84:87], v[144:147], v[176:179], v[84:87]
	v_mfma_f32_16x16x32_bf16 v[80:83], v[152:155], v[176:179], v[80:83]
	v_mfma_f32_16x16x32_bf16 v[68:71], v[144:147], v[180:183], v[68:71]
	v_mfma_f32_16x16x32_bf16 v[64:67], v[152:155], v[180:183], v[64:67]
	v_mfma_f32_16x16x32_bf16 v[116:119], v[148:151], v[168:171], v[116:119]
	v_mfma_f32_16x16x32_bf16 v[112:115], v[156:159], v[168:171], v[112:115]
	v_mfma_f32_16x16x32_bf16 v[100:103], v[148:151], v[172:175], v[100:103]
	v_mfma_f32_16x16x32_bf16 v[96:99], v[156:159], v[172:175], v[96:99]
	v_mfma_f32_16x16x32_bf16 v[84:87], v[148:151], v[184:187], v[84:87]
	v_mfma_f32_16x16x32_bf16 v[80:83], v[156:159], v[184:187], v[80:83]
	v_mfma_f32_16x16x32_bf16 v[68:71], v[148:151], v[188:191], v[68:71]
	v_mfma_f32_16x16x32_bf16 v[64:67], v[156:159], v[188:191], v[64:67]
	s_setprio 0
	s_barrier
	s_add_i32 s42, s67, s39
	s_add_i32 m0, s42, 0xffffff80
	ds_read_b128 v[160:163], v228 offset:49152
	ds_read_b128 v[164:167], v228 offset:51200
	ds_read_b128 v[168:171], v229 offset:49152
	ds_read_b128 v[172:175], v229 offset:51200
	ds_read_b128 v[176:179], v228 offset:53248
	ds_read_b128 v[180:183], v228 offset:55296
	ds_read_b128 v[184:187], v229 offset:53248
	ds_read_b128 v[188:191], v229 offset:55296
	global_load_lds_dwordx4 v194, s[40:41] offset:128
	s_add_i32 m0, s42, 0x1f80
	s_add_i32 s42, s68, s39
	global_load_lds_dwordx4 v198, s[40:41] offset:128
	s_add_u32 s40, s40, 0xb0080
	s_addc_u32 s41, s41, 0
	s_mov_b32 m0, s42
	s_nop 0
	global_load_lds_dwordx4 v194, s[40:41]
	s_add_i32 m0, s42, 0x2000
	s_nop 0
	global_load_lds_dwordx4 v198, s[40:41]
	s_add_i32 m0, s51, 0xffffff80
	s_nop 0
	global_load_lds_dwordx4 v192, s[98:99] offset:128
	s_add_i32 m0, s52, 0xffffff80
	s_nop 0
	global_load_lds_dwordx4 v196, s[98:99] offset:128
	s_waitcnt vmcnt(8)
	s_waitcnt lgkmcnt(0)
	s_barrier
	s_setprio 1
	s_waitcnt lgkmcnt(0)
	v_mfma_f32_16x16x32_bf16 v[60:63], v[120:123], v[160:163], v[60:63]
	v_mfma_f32_16x16x32_bf16 v[56:59], v[136:139], v[160:163], v[56:59]
	v_mfma_f32_16x16x32_bf16 v[44:47], v[120:123], v[164:167], v[44:47]
	v_mfma_f32_16x16x32_bf16 v[40:43], v[136:139], v[164:167], v[40:43]
	v_mfma_f32_16x16x32_bf16 v[28:31], v[120:123], v[176:179], v[28:31]
	v_mfma_f32_16x16x32_bf16 v[24:27], v[136:139], v[176:179], v[24:27]
	v_mfma_f32_16x16x32_bf16 v[12:15], v[120:123], v[180:183], v[12:15]
	v_mfma_f32_16x16x32_bf16 v[8:11], v[136:139], v[180:183], v[8:11]
	v_mfma_f32_16x16x32_bf16 v[60:63], v[128:131], v[168:171], v[60:63]
	v_mfma_f32_16x16x32_bf16 v[56:59], v[140:143], v[168:171], v[56:59]
	v_mfma_f32_16x16x32_bf16 v[44:47], v[128:131], v[172:175], v[44:47]
	v_mfma_f32_16x16x32_bf16 v[40:43], v[140:143], v[172:175], v[40:43]
	v_mfma_f32_16x16x32_bf16 v[28:31], v[128:131], v[184:187], v[28:31]
	v_mfma_f32_16x16x32_bf16 v[24:27], v[140:143], v[184:187], v[24:27]
	v_mfma_f32_16x16x32_bf16 v[12:15], v[128:131], v[188:191], v[12:15]
	v_mfma_f32_16x16x32_bf16 v[8:11], v[140:143], v[188:191], v[8:11]
	s_setprio 0
	s_setprio 1
	v_mfma_f32_16x16x32_bf16 v[52:55], v[144:147], v[160:163], v[52:55]
	v_mfma_f32_16x16x32_bf16 v[48:51], v[152:155], v[160:163], v[48:51]
	v_mfma_f32_16x16x32_bf16 v[36:39], v[144:147], v[164:167], v[36:39]
	v_mfma_f32_16x16x32_bf16 v[32:35], v[152:155], v[164:167], v[32:35]
	v_mfma_f32_16x16x32_bf16 v[20:23], v[144:147], v[176:179], v[20:23]
	v_mfma_f32_16x16x32_bf16 v[16:19], v[152:155], v[176:179], v[16:19]
	v_mfma_f32_16x16x32_bf16 v[4:7], v[144:147], v[180:183], v[4:7]
	v_mfma_f32_16x16x32_bf16 v[0:3], v[152:155], v[180:183], v[0:3]
	v_mfma_f32_16x16x32_bf16 v[52:55], v[148:151], v[168:171], v[52:55]
	v_mfma_f32_16x16x32_bf16 v[48:51], v[156:159], v[168:171], v[48:51]
	v_mfma_f32_16x16x32_bf16 v[36:39], v[148:151], v[172:175], v[36:39]
	v_mfma_f32_16x16x32_bf16 v[32:35], v[156:159], v[172:175], v[32:35]
	v_mfma_f32_16x16x32_bf16 v[20:23], v[148:151], v[184:187], v[20:23]
	v_mfma_f32_16x16x32_bf16 v[16:19], v[156:159], v[184:187], v[16:19]
	v_mfma_f32_16x16x32_bf16 v[4:7], v[148:151], v[188:191], v[4:7]
	v_mfma_f32_16x16x32_bf16 v[0:3], v[156:159], v[188:191], v[0:3]
	s_setprio 0
	s_barrier
	s_add_i32 s66, s66, 2
	s_add_u32 s4, s4, 0x100
	s_addc_u32 s5, s5, 0
	s_add_u32 s64, s64, 0x100
	s_addc_u32 s65, s65, 0
	s_cmp_gt_u32 s66, 41
	s_cbranch_scc0 .LBB0_1827
	s_branch .Lpx_6
.Lpeel_6:
	s_mov_b32 s100, 0
	ds_read_b128 v[120:123], v220
	ds_read_b128 v[128:131], v221
	ds_read_b128 v[136:139], v222
	ds_read_b128 v[140:143], v223
	ds_read_b128 v[144:147], v224
	ds_read_b128 v[148:151], v225
	ds_read_b128 v[152:155], v226
	ds_read_b128 v[156:159], v227
	s_add_u32 s40, s4, 0xfff50080
	s_addc_u32 s41, s5, -1
	s_cmp_eq_u32 s66, 40
	s_cselect_b32 s43, s29, s41
	s_cselect_b32 s42, s28, s40
	s_cselect_b32 s41, s35, s65
	s_cselect_b32 s40, s34, s64
	s_add_i32 m0, s44, 0xc000
	ds_read_b128 v[160:163], v228
	ds_read_b128 v[164:167], v228 offset:2048
	ds_read_b128 v[168:171], v229
	ds_read_b128 v[172:175], v229 offset:2048
	ds_read_b128 v[176:179], v228 offset:4096
	ds_read_b128 v[180:183], v228 offset:6144
	ds_read_b128 v[184:187], v229 offset:4096
	ds_read_b128 v[188:191], v229 offset:6144
	global_load_lds_dwordx4 v202, s[4:5]
	s_add_i32 m0, s44, 0xe000
	s_nop 0
	global_load_lds_dwordx4 v204, s[4:5]
	s_waitcnt vmcnt(8)
	s_waitcnt lgkmcnt(0)
	s_barrier
	s_setprio 1
	s_waitcnt lgkmcnt(0)
	v_mfma_f32_16x16x32_bf16 v[132:135], v[120:123], v[160:163], 0
	v_mfma_f32_16x16x32_bf16 v[124:127], v[136:139], v[160:163], 0
	v_mfma_f32_16x16x32_bf16 v[108:111], v[120:123], v[164:167], 0
	v_mfma_f32_16x16x32_bf16 v[104:107], v[136:139], v[164:167], 0
	v_mfma_f32_16x16x32_bf16 v[92:95], v[120:123], v[176:179], 0
	v_mfma_f32_16x16x32_bf16 v[88:91], v[136:139], v[176:179], 0
	v_mfma_f32_16x16x32_bf16 v[76:79], v[120:123], v[180:183], 0
	v_mfma_f32_16x16x32_bf16 v[72:75], v[136:139], v[180:183], 0
	v_mfma_f32_16x16x32_bf16 v[132:135], v[128:131], v[168:171], v[132:135]
	v_mfma_f32_16x16x32_bf16 v[124:127], v[140:143], v[168:171], v[124:127]
	v_mfma_f32_16x16x32_bf16 v[108:111], v[128:131], v[172:175], v[108:111]
	v_mfma_f32_16x16x32_bf16 v[104:107], v[140:143], v[172:175], v[104:107]
	v_mfma_f32_16x16x32_bf16 v[92:95], v[128:131], v[184:187], v[92:95]
	v_mfma_f32_16x16x32_bf16 v[88:91], v[140:143], v[184:187], v[88:91]
	v_mfma_f32_16x16x32_bf16 v[76:79], v[128:131], v[188:191], v[76:79]
	v_mfma_f32_16x16x32_bf16 v[72:75], v[140:143], v[188:191], v[72:75]
	s_setprio 0
	s_setprio 1
	v_mfma_f32_16x16x32_bf16 v[116:119], v[144:147], v[160:163], 0
	v_mfma_f32_16x16x32_bf16 v[112:115], v[152:155], v[160:163], 0
	v_mfma_f32_16x16x32_bf16 v[100:103], v[144:147], v[164:167], 0
	v_mfma_f32_16x16x32_bf16 v[96:99], v[152:155], v[164:167], 0
	v_mfma_f32_16x16x32_bf16 v[84:87], v[144:147], v[176:179], 0
	v_mfma_f32_16x16x32_bf16 v[80:83], v[152:155], v[176:179], 0
	v_mfma_f32_16x16x32_bf16 v[68:71], v[144:147], v[180:183], 0
	v_mfma_f32_16x16x32_bf16 v[64:67], v[152:155], v[180:183], 0
	v_mfma_f32_16x16x32_bf16 v[116:119], v[148:151], v[168:171], v[116:119]
	v_mfma_f32_16x16x32_bf16 v[112:115], v[156:159], v[168:171], v[112:115]
	v_mfma_f32_16x16x32_bf16 v[100:103], v[148:151], v[172:175], v[100:103]
	v_mfma_f32_16x16x32_bf16 v[96:99], v[156:159], v[172:175], v[96:99]
	v_mfma_f32_16x16x32_bf16 v[84:87], v[148:151], v[184:187], v[84:87]
	v_mfma_f32_16x16x32_bf16 v[80:83], v[156:159], v[184:187], v[80:83]
	v_mfma_f32_16x16x32_bf16 v[68:71], v[148:151], v[188:191], v[68:71]
	v_mfma_f32_16x16x32_bf16 v[64:67], v[156:159], v[188:191], v[64:67]
	s_setprio 0
	s_barrier
	s_add_i32 s67, s58, s39
	s_mov_b32 m0, s67
	ds_read_b128 v[160:163], v228 offset:16384
	ds_read_b128 v[164:167], v228 offset:18432
	ds_read_b128 v[168:171], v229 offset:16384
	ds_read_b128 v[172:175], v229 offset:18432
	ds_read_b128 v[176:179], v228 offset:20480
	ds_read_b128 v[180:183], v228 offset:22528
	ds_read_b128 v[184:187], v229 offset:20480
	ds_read_b128 v[188:191], v229 offset:22528
	global_load_lds_dwordx4 v194, s[40:41]
	s_add_i32 m0, s67, 0x2000
	s_add_u32 s68, s40, 0xb0000
	s_addc_u32 s69, s41, 0
	s_add_i32 s67, s59, s39
	global_load_lds_dwordx4 v198, s[40:41]
	s_mov_b32 m0, s67
	s_mov_b64 s[98:99], s[42:43]
	global_load_lds_dwordx4 v194, s[68:69]
	s_add_i32 m0, s67, 0x2000
	s_nop 0
	global_load_lds_dwordx4 v198, s[68:69]
	s_mov_b32 m0, s44
	s_nop 0
	global_load_lds_dwordx4 v192, s[42:43]
	s_mov_b32 m0, s45
	s_nop 0
	global_load_lds_dwordx4 v196, s[42:43]
	s_waitcnt vmcnt(8)
	s_waitcnt lgkmcnt(0)
	s_barrier
	s_setprio 1
	s_waitcnt lgkmcnt(0)
	v_mfma_f32_16x16x32_bf16 v[60:63], v[120:123], v[160:163], 0
	v_mfma_f32_16x16x32_bf16 v[56:59], v[136:139], v[160:163], 0
	v_mfma_f32_16x16x32_bf16 v[44:47], v[120:123], v[164:167], 0
	v_mfma_f32_16x16x32_bf16 v[40:43], v[136:139], v[164:167], 0
	v_mfma_f32_16x16x32_bf16 v[28:31], v[120:123], v[176:179], 0
	v_mfma_f32_16x16x32_bf16 v[24:27], v[136:139], v[176:179], 0
	v_mfma_f32_16x16x32_bf16 v[12:15], v[120:123], v[180:183], 0
	v_mfma_f32_16x16x32_bf16 v[8:11], v[136:139], v[180:183], 0
	v_mfma_f32_16x16x32_bf16 v[60:63], v[128:131], v[168:171], v[60:63]
	v_mfma_f32_16x16x32_bf16 v[56:59], v[140:143], v[168:171], v[56:59]
	v_mfma_f32_16x16x32_bf16 v[44:47], v[128:131], v[172:175], v[44:47]
	v_mfma_f32_16x16x32_bf16 v[40:43], v[140:143], v[172:175], v[40:43]
	v_mfma_f32_16x16x32_bf16 v[28:31], v[128:131], v[184:187], v[28:31]
	v_mfma_f32_16x16x32_bf16 v[24:27], v[140:143], v[184:187], v[24:27]
	v_mfma_f32_16x16x32_bf16 v[12:15], v[128:131], v[188:191], v[12:15]
	v_mfma_f32_16x16x32_bf16 v[8:11], v[140:143], v[188:191], v[8:11]
	s_setprio 0
	s_setprio 1
	v_mfma_f32_16x16x32_bf16 v[52:55], v[144:147], v[160:163], 0
	v_mfma_f32_16x16x32_bf16 v[48:51], v[152:155], v[160:163], 0
	v_mfma_f32_16x16x32_bf16 v[36:39], v[144:147], v[164:167], 0
	v_mfma_f32_16x16x32_bf16 v[32:35], v[152:155], v[164:167], 0
	v_mfma_f32_16x16x32_bf16 v[20:23], v[144:147], v[176:179], 0
	v_mfma_f32_16x16x32_bf16 v[16:19], v[152:155], v[176:179], 0
	v_mfma_f32_16x16x32_bf16 v[4:7], v[144:147], v[180:183], 0
	v_mfma_f32_16x16x32_bf16 v[0:3], v[152:155], v[180:183], 0
	v_mfma_f32_16x16x32_bf16 v[52:55], v[148:151], v[168:171], v[52:55]
	v_mfma_f32_16x16x32_bf16 v[48:51], v[156:159], v[168:171], v[48:51]
	v_mfma_f32_16x16x32_bf16 v[36:39], v[148:151], v[172:175], v[36:39]
	v_mfma_f32_16x16x32_bf16 v[32:35], v[156:159], v[172:175], v[32:35]
	v_mfma_f32_16x16x32_bf16 v[20:23], v[148:151], v[184:187], v[20:23]
	v_mfma_f32_16x16x32_bf16 v[16:19], v[156:159], v[184:187], v[16:19]
	v_mfma_f32_16x16x32_bf16 v[4:7], v[148:151], v[188:191], v[4:7]
	v_mfma_f32_16x16x32_bf16 v[0:3], v[156:159], v[188:191], v[0:3]
	s_setprio 0
	s_barrier
	s_add_i32 s67, 0, 0x18000
	s_add_i32 s68, 0, 0x1c000
	ds_read_b128 v[120:123], v245 offset:32768
	ds_read_b128 v[128:131], v246 offset:32768
	ds_read_b128 v[136:139], v230
	ds_read_b128 v[140:143], v231
	ds_read_b128 v[144:147], v245 offset:49152
	ds_read_b128 v[148:151], v246 offset:49152
	ds_read_b128 v[152:155], v232
	ds_read_b128 v[156:159], v233
	s_add_u32 s42, s42, 0xb0000
	s_addc_u32 s43, s43, 0
	s_mov_b32 m0, s46
	ds_read_b128 v[160:163], v228 offset:32768
	ds_read_b128 v[164:167], v228 offset:34816
	ds_read_b128 v[168:171], v229 offset:32768
	ds_read_b128 v[172:175], v229 offset:34816
	ds_read_b128 v[176:179], v228 offset:36864
	ds_read_b128 v[180:183], v228 offset:38912
	ds_read_b128 v[184:187], v229 offset:36864
	ds_read_b128 v[188:191], v229 offset:38912
	global_load_lds_dwordx4 v192, s[42:43]
	s_mov_b32 m0, s47
	s_nop 0
	global_load_lds_dwordx4 v196, s[42:43]
	s_waitcnt vmcnt(8)
	s_waitcnt lgkmcnt(0)
	s_barrier
	s_setprio 1
	s_waitcnt lgkmcnt(0)
	v_mfma_f32_16x16x32_bf16 v[132:135], v[120:123], v[160:163], v[132:135]
	v_mfma_f32_16x16x32_bf16 v[124:127], v[136:139], v[160:163], v[124:127]
	v_mfma_f32_16x16x32_bf16 v[108:111], v[120:123], v[164:167], v[108:111]
	v_mfma_f32_16x16x32_bf16 v[104:107], v[136:139], v[164:167], v[104:107]
	v_mfma_f32_16x16x32_bf16 v[92:95], v[120:123], v[176:179], v[92:95]
	v_mfma_f32_16x16x32_bf16 v[88:91], v[136:139], v[176:179], v[88:91]
	v_mfma_f32_16x16x32_bf16 v[76:79], v[120:123], v[180:183], v[76:79]
	v_mfma_f32_16x16x32_bf16 v[72:75], v[136:139], v[180:183], v[72:75]
	v_mfma_f32_16x16x32_bf16 v[132:135], v[128:131], v[168:171], v[132:135]
	v_mfma_f32_16x16x32_bf16 v[124:127], v[140:143], v[168:171], v[124:127]
	v_mfma_f32_16x16x32_bf16 v[108:111], v[128:131], v[172:175], v[108:111]
	v_mfma_f32_16x16x32_bf16 v[104:107], v[140:143], v[172:175], v[104:107]
	v_mfma_f32_16x16x32_bf16 v[92:95], v[128:131], v[184:187], v[92:95]
	v_mfma_f32_16x16x32_bf16 v[88:91], v[140:143], v[184:187], v[88:91]
	v_mfma_f32_16x16x32_bf16 v[76:79], v[128:131], v[188:191], v[76:79]
	v_mfma_f32_16x16x32_bf16 v[72:75], v[140:143], v[188:191], v[72:75]
	s_setprio 0
	s_setprio 1
	v_mfma_f32_16x16x32_bf16 v[116:119], v[144:147], v[160:163], v[116:119]
	v_mfma_f32_16x16x32_bf16 v[112:115], v[152:155], v[160:163], v[112:115]
	v_mfma_f32_16x16x32_bf16 v[100:103], v[144:147], v[164:167], v[100:103]
	v_mfma_f32_16x16x32_bf16 v[96:99], v[152:155], v[164:167], v[96:99]
	v_mfma_f32_16x16x32_bf16 v[84:87], v[144:147], v[176:179], v[84:87]
	v_mfma_f32_16x16x32_bf16 v[80:83], v[152:155], v[176:179], v[80:83]
	v_mfma_f32_16x16x32_bf16 v[68:71], v[144:147], v[180:183], v[68:71]
	v_mfma_f32_16x16x32_bf16 v[64:67], v[152:155], v[180:183], v[64:67]
	v_mfma_f32_16x16x32_bf16 v[116:119], v[148:151], v[168:171], v[116:119]
	v_mfma_f32_16x16x32_bf16 v[112:115], v[156:159], v[168:171], v[112:115]
	v_mfma_f32_16x16x32_bf16 v[100:103], v[148:151], v[172:175], v[100:103]
	v_mfma_f32_16x16x32_bf16 v[96:99], v[156:159], v[172:175], v[96:99]
	v_mfma_f32_16x16x32_bf16 v[84:87], v[148:151], v[184:187], v[84:87]
	v_mfma_f32_16x16x32_bf16 v[80:83], v[156:159], v[184:187], v[80:83]
	v_mfma_f32_16x16x32_bf16 v[68:71], v[148:151], v[188:191], v[68:71]
	v_mfma_f32_16x16x32_bf16 v[64:67], v[156:159], v[188:191], v[64:67]
	s_setprio 0
	s_barrier
	s_add_i32 s42, s67, s39
	s_add_i32 m0, s42, 0xffffff80
	ds_read_b128 v[160:163], v228 offset:49152
	ds_read_b128 v[164:167], v228 offset:51200
	ds_read_b128 v[168:171], v229 offset:49152
	ds_read_b128 v[172:175], v229 offset:51200
	ds_read_b128 v[176:179], v228 offset:53248
	ds_read_b128 v[180:183], v228 offset:55296
	ds_read_b128 v[184:187], v229 offset:53248
	ds_read_b128 v[188:191], v229 offset:55296
	global_load_lds_dwordx4 v194, s[40:41] offset:128
	s_add_i32 m0, s42, 0x1f80
	s_add_i32 s42, s68, s39
	global_load_lds_dwordx4 v198, s[40:41] offset:128
	s_add_u32 s40, s40, 0xb0080
	s_addc_u32 s41, s41, 0
	s_mov_b32 m0, s42
	s_nop 0
	global_load_lds_dwordx4 v194, s[40:41]
	s_add_i32 m0, s42, 0x2000
	s_nop 0
	global_load_lds_dwordx4 v198, s[40:41]
	s_add_i32 m0, s51, 0xffffff80
	s_nop 0
	global_load_lds_dwordx4 v192, s[98:99] offset:128
	s_add_i32 m0, s52, 0xffffff80
	s_nop 0
	global_load_lds_dwordx4 v196, s[98:99] offset:128
	s_waitcnt vmcnt(8)
	s_waitcnt lgkmcnt(0)
	s_barrier
	s_setprio 1
	s_waitcnt lgkmcnt(0)
	v_mfma_f32_16x16x32_bf16 v[60:63], v[120:123], v[160:163], v[60:63]
	v_mfma_f32_16x16x32_bf16 v[56:59], v[136:139], v[160:163], v[56:59]
	v_mfma_f32_16x16x32_bf16 v[44:47], v[120:123], v[164:167], v[44:47]
	v_mfma_f32_16x16x32_bf16 v[40:43], v[136:139], v[164:167], v[40:43]
	v_mfma_f32_16x16x32_bf16 v[28:31], v[120:123], v[176:179], v[28:31]
	v_mfma_f32_16x16x32_bf16 v[24:27], v[136:139], v[176:179], v[24:27]
	v_mfma_f32_16x16x32_bf16 v[12:15], v[120:123], v[180:183], v[12:15]
	v_mfma_f32_16x16x32_bf16 v[8:11], v[136:139], v[180:183], v[8:11]
	v_mfma_f32_16x16x32_bf16 v[60:63], v[128:131], v[168:171], v[60:63]
	v_mfma_f32_16x16x32_bf16 v[56:59], v[140:143], v[168:171], v[56:59]
	v_mfma_f32_16x16x32_bf16 v[44:47], v[128:131], v[172:175], v[44:47]
	v_mfma_f32_16x16x32_bf16 v[40:43], v[140:143], v[172:175], v[40:43]
	v_mfma_f32_16x16x32_bf16 v[28:31], v[128:131], v[184:187], v[28:31]
	v_mfma_f32_16x16x32_bf16 v[24:27], v[140:143], v[184:187], v[24:27]
	v_mfma_f32_16x16x32_bf16 v[12:15], v[128:131], v[188:191], v[12:15]
	v_mfma_f32_16x16x32_bf16 v[8:11], v[140:143], v[188:191], v[8:11]
	s_setprio 0
	s_setprio 1
	v_mfma_f32_16x16x32_bf16 v[52:55], v[144:147], v[160:163], v[52:55]
	v_mfma_f32_16x16x32_bf16 v[48:51], v[152:155], v[160:163], v[48:51]
	v_mfma_f32_16x16x32_bf16 v[36:39], v[144:147], v[164:167], v[36:39]
	v_mfma_f32_16x16x32_bf16 v[32:35], v[152:155], v[164:167], v[32:35]
	v_mfma_f32_16x16x32_bf16 v[20:23], v[144:147], v[176:179], v[20:23]
	v_mfma_f32_16x16x32_bf16 v[16:19], v[152:155], v[176:179], v[16:19]
	v_mfma_f32_16x16x32_bf16 v[4:7], v[144:147], v[180:183], v[4:7]
	v_mfma_f32_16x16x32_bf16 v[0:3], v[152:155], v[180:183], v[0:3]
	v_mfma_f32_16x16x32_bf16 v[52:55], v[148:151], v[168:171], v[52:55]
	v_mfma_f32_16x16x32_bf16 v[48:51], v[156:159], v[168:171], v[48:51]
	v_mfma_f32_16x16x32_bf16 v[36:39], v[148:151], v[172:175], v[36:39]
	v_mfma_f32_16x16x32_bf16 v[32:35], v[156:159], v[172:175], v[32:35]
	v_mfma_f32_16x16x32_bf16 v[20:23], v[148:151], v[184:187], v[20:23]
	v_mfma_f32_16x16x32_bf16 v[16:19], v[156:159], v[184:187], v[16:19]
	v_mfma_f32_16x16x32_bf16 v[4:7], v[148:151], v[188:191], v[4:7]
	v_mfma_f32_16x16x32_bf16 v[0:3], v[156:159], v[188:191], v[0:3]
	s_setprio 0
	s_barrier
	s_add_i32 s66, s66, 2
	s_add_u32 s4, s4, 0x100
	s_addc_u32 s5, s5, 0
	s_add_u32 s64, s64, 0x100
	s_addc_u32 s65, s65, 0
	s_cmp_gt_u32 s66, 41
	s_cbranch_scc0 .LBB0_1827
